# cross-attention output stores: plain -> sc0 sc1 write-through (no dirty lines for the barrier write-back before the xo GEMM)
# baseline (speedup 1.0000x reference)
; DI void xattn_unit(const bf16_t* __restrict__ Qg, const bf16_t* __restrict__ Kg, const bf16_t* __restrict__ Vg, bf16_t* __restrict__ Og, lds_t* shm) {
;     ...
;   const int tid = tidx(), lane = tid & 63, h = lane >> 5, l31 = lane & 31, wid = __builtin_amdgcn_readfirstlane(tid >> 6);
;   unsigned soff[2];
; #pragma unroll
;   for (int i = 0; i < 2; ++i) { unsigned r, c; inv_off_a(tid + 512 * i, r, c); soff[i] = (r * (unsigned)LDKV + c * 8u) * 2u; }
;   constexpr unsigned tstep = 64u * LDKV * 2u;
;   auto issue_tile = [&](const bf16_t* src, int t, unsigned lds_base) __attribute__((always_inline)) {
;     const char* sb = (const char*)src + (size_t)t * tstep; lds_t* base = shm + lds_base + wid * 1024;
; #pragma unroll
;     for (int im = 0; im < 2; ++im) { glds16(sb + im * 256, soff[0], base + im * 16384); glds16(sb + im * 256, soff[1], base + im * 16384 + 8192); }
;   };
;   __syncthreads();
; #pragma unroll
;   for (int t = 0; t < 4; ++t) issue_tile(Kg, t, t * 32768);
;   issue_tile(Vg, 0, 131072);
;   const unsigned q4 = (lane & 15) >> 2, pp = lane & 3, blk = (lane >> 4) & 1;
;   const unsigned xk = (l31 >> 2) & 3, kbase = 2048u * (l31 >> 3) + 64u * (l31 & 7);
;   const unsigned ka0 = kbase + 16u * ((unsigned)h ^ xk), ka2 = kbase + 16u * ((2u + h) ^ xk);
;   const unsigned vrow = 64u * (4u * h + q4), cl = 2u * blk + (pp >> 1);
;   const unsigned va0 = vrow + 16u * (cl ^ (unsigned)h) + 8u * (pp & 1), va1 = vrow + 16u * (cl ^ ((unsigned)h ^ 2u)) + 8u * (pp & 1);
;   const unsigned qoff = ((unsigned)l31 * (unsigned)LDQ + 8u * h) * 2u;
;   f32x16 S[4][2];
; #pragma unroll
;   for (int t = 0; t < 4; ++t)
; #pragma unroll
;     for (int kb = 0; kb < 2; ++kb)
; #pragma unroll
;       for (int i = 0; i < 16; ++i) S[t][kb][i] = 0.f;
; DI void cross_attn_own_tiles(const Params& p, lds_t* shm) {
;   const int wid = __builtin_amdgcn_readfirstlane(tidx() >> 6);
;   const bf16_t* Q = slot(p, 3); const bf16_t* KV = (const bf16_t*)(p.ws + OFF_KVX); bf16_t* O = slot(p, 0);
;   for (int i = 0;; ++i) {
;     int pm, pn; if (!g8::tile_coords(i * (int)gridDim.x + (int)blockIdx.x, T_TOK / 256, 4, pm, pn)) break;
;     const int b = pm >> 5, hd = pn; const size_t r0 = (size_t)pm * 256 + wid * 32;
;     xattn_unit(Q + r0 * DM + hd * 256, KV + (size_t)b * 256 * 2048 + hd * 256, KV + (size_t)b * 256 * 2048 + 1024 + hd * 256, O + r0 * DM + hd * 256, shm);
.LBB0_629:
	s_add_i32 s0, s29, s0
	s_ashr_i32 s1, s0, 31
	s_lshr_b32 s1, s1, 27
	s_add_i32 s1, s0, s1
	s_ashr_i32 s28, s1, 5
	s_and_b32 s1, s1, 0xffe0
	s_sub_i32 s0, s0, s1
	s_bfe_i32 s1, s0, 0x80000
	s_bfe_u32 s1, s1, 0x3000c
	s_add_i32 s1, s0, s1
	s_bfe_i32 s29, s1, 0x80000
	s_and_b32 s1, s1, 0xf8
	s_sub_i32 s0, s0, s1
	s_lshl_b32 s28, s28, 3
	s_sext_i32_i8 s0, s0
	s_add_i32 s0, s28, s0
	s_ashr_i32 s1, s0, 31
	s_ashr_i32 s28, s0, 5
	s_lshl_b64 s[0:1], s[0:1], 18
	s_add_u32 s0, s0, s4
	s_addc_u32 s1, s1, s5
	s_lshl_b64 s[0:1], s[0:1], 1
	s_sext_i32_i16 s29, s29
	s_add_u32 s36, s26, s0
	s_addc_u32 s37, s27, s1
	s_lshl_b32 s29, s29, 5
	s_and_b32 s30, s29, 0xffffff00
	s_ashr_i32 s31, s30, 31
	s_lshl_b64 s[30:31], s[30:31], 1
	s_add_u32 s38, s36, s30
	s_addc_u32 s39, s37, s31
	s_ashr_i32 s29, s28, 31
	s_lshl_b64 s[28:29], s[28:29], 20
	s_add_u32 s28, s50, s28
	s_addc_u32 s29, s51, s29
	s_add_u32 s36, s28, s30
	s_addc_u32 s37, s29, s31
	s_add_u32 s0, s44, s0
	s_addc_u32 s1, s45, s1
	s_add_u32 s30, s0, s30
	v_mov_b32_e32 v6, v212
	s_addc_u32 s31, s1, s31
	s_mov_b32 s1, 0xfffff8
	v_bfe_u32 v1, v6, 2, 3
	v_lshrrev_b32_e32 v2, 4, v6
	v_and_or_b32 v2, v2, s1, v1
	v_lshrrev_b32_e32 v8, 3, v6
	v_lshrrev_b32_e32 v3, 2, v2
	v_and_b32_e32 v0, 12, v8
	v_xor_b32_e32 v3, v3, v6
	v_lshlrev_b32_e32 v7, 4, v6
	v_and_or_b32 v3, v3, 3, v0
	v_lshlrev_b32_e32 v2, 12, v2
	v_lshl_or_b32 v160, v3, 4, v2
	v_add_u32_e32 v2, 0x2000, v7
	v_readfirstlane_b32 s0, v6
	v_lshrrev_b32_e32 v2, 8, v2
	v_and_or_b32 v1, v2, s1, v1
	s_lshl_b32 s0, s0, 4
	v_lshrrev_b32_e32 v2, 2, v1
	s_and_b32 s82, s0, 0xfffffc00
	v_xor_b32_e32 v2, v2, v6
	s_add_i32 s78, s82, 0
	v_and_or_b32 v0, v2, 3, v0
	v_lshlrev_b32_e32 v1, 12, v1
	s_mov_b32 m0, s78
	v_lshl_or_b32 v162, v0, 4, v1
	s_barrier
	v_lshl_add_u64 v[0:1], s[36:37], 0, v[160:161]
	global_load_lds_dwordx4 v160, s[36:37]
	s_add_i32 m0, s78, 0x2000
	s_mov_b64 s[0:1], 0x100
	global_load_lds_dwordx4 v162, s[36:37]
	s_add_i32 m0, s78, 0x4000
	v_lshl_add_u64 v[4:5], v[0:1], 0, s[0:1]
	v_mov_b32_e32 v163, v161
	global_load_lds_dwordx4 v[4:5], off
	s_add_i32 m0, s78, 0x6000
	v_lshl_add_u64 v[2:3], s[36:37], 0, v[162:163]
	s_add_u32 s28, s36, 0x40000
	v_lshl_add_u64 v[4:5], v[2:3], 0, s[0:1]
	s_addc_u32 s29, s37, 0
	s_add_i32 s67, s78, 0x8000
	global_load_lds_dwordx4 v[4:5], off
	s_mov_b32 m0, s67
	s_add_i32 s0, s78, 0xa000
	global_load_lds_dwordx4 v160, s[28:29]
	s_mov_b32 m0, s0
	v_bfe_u32 v163, v6, 5, 1
	global_load_lds_dwordx4 v162, s[28:29]
	s_add_u32 s28, s36, 0x40100
	s_addc_u32 s29, s37, 0
	s_add_i32 s1, s78, 0xc000
	s_add_i32 vcc_lo, s78, 0xe000
	s_mov_b32 m0, s1
	s_add_u32 s68, s36, 0x80000
	global_load_lds_dwordx4 v160, s[28:29]
	s_mov_b32 m0, vcc_lo
	s_addc_u32 s69, s37, 0
	s_add_i32 vcc_hi, s78, 0x10000
	global_load_lds_dwordx4 v162, s[28:29]
	s_mov_b32 m0, vcc_hi
	s_add_i32 s28, s78, 0x12000
	global_load_lds_dwordx4 v160, s[68:69]
	s_mov_b32 m0, s28
	s_add_u32 s76, s36, 0x80100
	global_load_lds_dwordx4 v162, s[68:69]
	s_addc_u32 s77, s37, 0
	s_add_i32 s29, s78, 0x14000
	s_add_i32 s68, s78, 0x16000
	s_mov_b32 m0, s29
	s_add_u32 s80, s36, 0xc0000
	global_load_lds_dwordx4 v160, s[76:77]
	s_mov_b32 m0, s68
	s_addc_u32 s81, s37, 0
	s_add_i32 s69, s78, 0x18000
	global_load_lds_dwordx4 v162, s[76:77]
	s_mov_b32 m0, s69
	s_add_i32 s76, s78, 0x1a000
	global_load_lds_dwordx4 v160, s[80:81]
	s_mov_b32 m0, s76
	v_and_b32_e32 v132, 0xc0, v7
	global_load_lds_dwordx4 v162, s[80:81]
	s_add_u32 s80, s36, 0xc0100
	s_addc_u32 s81, s37, 0
	s_add_i32 s77, s78, 0x1c000
	s_mov_b32 m0, s77
	s_add_i32 s78, s78, 0x1e000
	global_load_lds_dwordx4 v160, s[80:81]
	s_mov_b32 m0, s78
	s_add_i32 s79, s14, s82
	global_load_lds_dwordx4 v162, s[80:81]
	s_mov_b64 s[80:81], 0x800
	v_lshl_add_u64 v[4:5], v[0:1], 0, s[80:81]
	s_mov_b32 m0, s79
	v_or_b32_e32 v7, 2, v163
	global_load_lds_dwordx4 v[4:5], off
	s_add_i32 m0, s79, 0x2000
	v_lshl_add_u64 v[4:5], v[2:3], 0, s[80:81]
	s_mov_b64 s[80:81], 0x900
	global_load_lds_dwordx4 v[4:5], off
	s_add_i32 m0, s79, 0x4000
	v_lshl_add_u64 v[0:1], v[0:1], 0, s[80:81]
	global_load_lds_dwordx4 v[0:1], off
	s_add_i32 m0, s79, 0x6000
	v_lshl_add_u64 v[0:1], v[2:3], 0, s[80:81]
	global_load_lds_dwordx4 v[0:1], off
	v_lshlrev_b32_e32 v1, 6, v6
	v_and_b32_e32 v5, 0x1c0, v1
	v_and_b32_e32 v1, 2, v8
	v_bfe_u32 v2, v6, 1, 1
	v_bitop3_b32 v3, v1, v163, v2 bitop3:0x36
	v_bitop3_b32 v1, v1, v7, v2 bitop3:0x36
	s_waitcnt vmcnt(0)
	v_lshlrev_b32_e32 v165, 4, v1
	v_lshlrev_b32_e32 v1, 11, v6
	v_lshlrev_b32_e32 v0, 8, v6
	v_and_b32_e32 v164, 0xf800, v1
	v_lshrrev_b32_e32 v4, 5, v6
	v_lshlrev_b32_e32 v169, 3, v6
	v_bfe_u32 v130, v6, 2, 2
	v_and_b32_e32 v6, 0x1800, v0
	v_lshlrev_b32_e32 v166, 4, v3
	v_lshl_or_b32 v128, v163, 4, v164
	s_waitcnt vmcnt(0) lgkmcnt(0)
	s_barrier
; #define LDSP(T, p) ((__attribute__((address_space(3))) T*)(p))
; #define MFMA32(a, b, c) __builtin_amdgcn_mfma_f32_32x32x16_bf16((a), (b), (c), 0, 0, 0)
; DI void xattn_unit(const bf16_t* __restrict__ Qg, const bf16_t* __restrict__ Kg, const bf16_t* __restrict__ Vg, bf16_t* __restrict__ Og, lds_t* shm) {
;     ...
; #pragma unroll
;   for (int ss = 0; ss < 16; ++ss) {
;     const int cgl = 2 * ss, img = cgl >> 4;
;     const bf16x8 qv = gld<bf16x8>(Qg + 16 * ss, qoff);
; #pragma unroll
;     for (int t = 0; t < 4; ++t)
; #pragma unroll
;       for (int kb = 0; kb < 2; ++kb) {
;         const bf16x8 kf = *LDSP(const bf16x8, shm + t * 32768 + img * 16384 + kb * 8192 + 512 * ((cgl & 15) >> 2) + ((cgl & 2) ? ka2 : ka0));
;         S[t][kb] = MFMA32(kf, qv, S[t][kb]);
;       }
;   }
	global_load_dwordx4 v[172:175], v128, s[38:39]
	global_load_dwordx4 v[176:179], v128, s[38:39] offset:32
	global_load_dwordx4 v[180:183], v128, s[38:39] offset:64
	global_load_dwordx4 v[184:187], v128, s[38:39] offset:96
	global_load_dwordx4 v[188:191], v128, s[38:39] offset:128
	global_load_dwordx4 v[192:195], v128, s[38:39] offset:160
	global_load_dwordx4 v[196:199], v128, s[38:39] offset:192
	global_load_dwordx4 v[200:203], v128, s[38:39] offset:224
	global_load_dwordx4 v[204:207], v128, s[38:39] offset:256
	global_load_dwordx4 v[208:211], v128, s[38:39] offset:288
	global_load_dwordx4 v[216:219], v128, s[38:39] offset:320
	global_load_dwordx4 v[220:223], v128, s[38:39] offset:352
	global_load_dwordx4 v[224:227], v128, s[38:39] offset:384
	global_load_dwordx4 v[228:231], v128, s[38:39] offset:416
	global_load_dwordx4 v[232:235], v128, s[38:39] offset:448
	global_load_dwordx4 v[236:239], v128, s[38:39] offset:480
	v_bitop3_b32 v4, v4, v130, 1 bitop3:0x6c
	v_add3_u32 v131, 0, v6, v5
	v_lshl_add_u32 v129, v4, 4, v131
	v_bitop3_b32 v130, v163, v130, 2 bitop3:0x36
	v_lshl_add_u32 v133, v130, 4, v131
	v_lshl_or_b32 v170, v163, 8, v132
	v_add_u32_e32 v248, 0x10000, v129
	v_add_u32_e32 v249, 0x10000, v133
	ds_read_b128 v[144:147], v129
	ds_read_b128 v[148:151], v129 offset:8192
	ds_read_b128 v[152:155], v129 offset:32768
	ds_read_b128 v[156:159], v129 offset:40960
	s_waitcnt vmcnt(15) lgkmcnt(3)
	v_mfma_f32_32x32x16_bf16 v[112:127], v[144:147], v[172:175], 0
	ds_read_b128 v[144:147], v248
	s_waitcnt lgkmcnt(3)
	v_mfma_f32_32x32x16_bf16 v[96:111], v[148:151], v[172:175], 0
	ds_read_b128 v[148:151], v248 offset:8192
	s_waitcnt lgkmcnt(3)
	v_mfma_f32_32x32x16_bf16 v[80:95], v[152:155], v[172:175], 0
	ds_read_b128 v[152:155], v248 offset:32768
	s_waitcnt lgkmcnt(3)
	v_mfma_f32_32x32x16_bf16 v[64:79], v[156:159], v[172:175], 0
	ds_read_b128 v[156:159], v248 offset:40960
	s_waitcnt lgkmcnt(3)
	v_mfma_f32_32x32x16_bf16 v[48:63], v[144:147], v[172:175], 0
	ds_read_b128 v[144:147], v133
	s_waitcnt lgkmcnt(3)
	v_mfma_f32_32x32x16_bf16 v[32:47], v[148:151], v[172:175], 0
	ds_read_b128 v[148:151], v133 offset:8192
	s_waitcnt lgkmcnt(3)
	v_mfma_f32_32x32x16_bf16 v[16:31], v[152:155], v[172:175], 0
	ds_read_b128 v[152:155], v133 offset:32768
	s_waitcnt lgkmcnt(3)
	v_mfma_f32_32x32x16_bf16 v[0:15], v[156:159], v[172:175], 0
	ds_read_b128 v[156:159], v133 offset:40960
	s_waitcnt vmcnt(14) lgkmcnt(3)
	v_mfma_f32_32x32x16_bf16 v[112:127], v[144:147], v[176:179], v[112:127]
	ds_read_b128 v[144:147], v249
	s_waitcnt lgkmcnt(3)
	v_mfma_f32_32x32x16_bf16 v[96:111], v[148:151], v[176:179], v[96:111]
	ds_read_b128 v[148:151], v249 offset:8192
	s_waitcnt lgkmcnt(3)
	v_mfma_f32_32x32x16_bf16 v[80:95], v[152:155], v[176:179], v[80:95]
	ds_read_b128 v[152:155], v249 offset:32768
	s_waitcnt lgkmcnt(3)
	v_mfma_f32_32x32x16_bf16 v[64:79], v[156:159], v[176:179], v[64:79]
	ds_read_b128 v[156:159], v249 offset:40960
	s_waitcnt lgkmcnt(3)
	v_mfma_f32_32x32x16_bf16 v[48:63], v[144:147], v[176:179], v[48:63]
	ds_read_b128 v[144:147], v129 offset:512
	s_waitcnt lgkmcnt(3)
	v_mfma_f32_32x32x16_bf16 v[32:47], v[148:151], v[176:179], v[32:47]
	ds_read_b128 v[148:151], v129 offset:8704
	s_waitcnt lgkmcnt(3)
	v_mfma_f32_32x32x16_bf16 v[16:31], v[152:155], v[176:179], v[16:31]
	ds_read_b128 v[152:155], v129 offset:33280
	s_waitcnt lgkmcnt(3)
	v_mfma_f32_32x32x16_bf16 v[0:15], v[156:159], v[176:179], v[0:15]
	ds_read_b128 v[156:159], v129 offset:41472
	s_waitcnt vmcnt(13) lgkmcnt(3)
	v_mfma_f32_32x32x16_bf16 v[112:127], v[144:147], v[180:183], v[112:127]
	ds_read_b128 v[144:147], v248 offset:512
	s_waitcnt lgkmcnt(3)
	v_mfma_f32_32x32x16_bf16 v[96:111], v[148:151], v[180:183], v[96:111]
	ds_read_b128 v[148:151], v248 offset:8704
	s_waitcnt lgkmcnt(3)
	v_mfma_f32_32x32x16_bf16 v[80:95], v[152:155], v[180:183], v[80:95]
	ds_read_b128 v[152:155], v248 offset:33280
	s_waitcnt lgkmcnt(3)
	v_mfma_f32_32x32x16_bf16 v[64:79], v[156:159], v[180:183], v[64:79]
	ds_read_b128 v[156:159], v248 offset:41472
	s_waitcnt lgkmcnt(3)
	v_mfma_f32_32x32x16_bf16 v[48:63], v[144:147], v[180:183], v[48:63]
	ds_read_b128 v[144:147], v133 offset:512
	s_waitcnt lgkmcnt(3)
	v_mfma_f32_32x32x16_bf16 v[32:47], v[148:151], v[180:183], v[32:47]
	ds_read_b128 v[148:151], v133 offset:8704
	s_waitcnt lgkmcnt(3)
	v_mfma_f32_32x32x16_bf16 v[16:31], v[152:155], v[180:183], v[16:31]
	ds_read_b128 v[152:155], v133 offset:33280
	s_waitcnt lgkmcnt(3)
	v_mfma_f32_32x32x16_bf16 v[0:15], v[156:159], v[180:183], v[0:15]
	ds_read_b128 v[156:159], v133 offset:41472
	s_waitcnt vmcnt(12) lgkmcnt(3)
	v_mfma_f32_32x32x16_bf16 v[112:127], v[144:147], v[184:187], v[112:127]
	ds_read_b128 v[144:147], v249 offset:512
	s_waitcnt lgkmcnt(3)
	v_mfma_f32_32x32x16_bf16 v[96:111], v[148:151], v[184:187], v[96:111]
	ds_read_b128 v[148:151], v249 offset:8704
	s_waitcnt lgkmcnt(3)
	v_mfma_f32_32x32x16_bf16 v[80:95], v[152:155], v[184:187], v[80:95]
	ds_read_b128 v[152:155], v249 offset:33280
	s_waitcnt lgkmcnt(3)
	v_mfma_f32_32x32x16_bf16 v[64:79], v[156:159], v[184:187], v[64:79]
	ds_read_b128 v[156:159], v249 offset:41472
	s_waitcnt lgkmcnt(3)
	v_mfma_f32_32x32x16_bf16 v[48:63], v[144:147], v[184:187], v[48:63]
	ds_read_b128 v[144:147], v129 offset:1024
	s_waitcnt lgkmcnt(3)
	v_mfma_f32_32x32x16_bf16 v[32:47], v[148:151], v[184:187], v[32:47]
	ds_read_b128 v[148:151], v129 offset:9216
	s_waitcnt lgkmcnt(3)
	v_mfma_f32_32x32x16_bf16 v[16:31], v[152:155], v[184:187], v[16:31]
	ds_read_b128 v[152:155], v129 offset:33792
	s_waitcnt lgkmcnt(3)
	v_mfma_f32_32x32x16_bf16 v[0:15], v[156:159], v[184:187], v[0:15]
	ds_read_b128 v[156:159], v129 offset:41984
	s_waitcnt vmcnt(11) lgkmcnt(3)
; #define LDSP(T, p) ((__attribute__((address_space(3))) T*)(p))
; #define MFMA32(a, b, c) __builtin_amdgcn_mfma_f32_32x32x16_bf16((a), (b), (c), 0, 0, 0)
; DI void xattn_unit(const bf16_t* __restrict__ Qg, const bf16_t* __restrict__ Kg, const bf16_t* __restrict__ Vg, bf16_t* __restrict__ Og, lds_t* shm) {
;     ...
; #pragma unroll
;   for (int ss = 0; ss < 16; ++ss) {
;     const int cgl = 2 * ss, img = cgl >> 4;
;     const bf16x8 qv = gld<bf16x8>(Qg + 16 * ss, qoff);
; #pragma unroll
;     for (int t = 0; t < 4; ++t)
; #pragma unroll
;       for (int kb = 0; kb < 2; ++kb) {
;         const bf16x8 kf = *LDSP(const bf16x8, shm + t * 32768 + img * 16384 + kb * 8192 + 512 * ((cgl & 15) >> 2) + ((cgl & 2) ? ka2 : ka0));
;         S[t][kb] = MFMA32(kf, qv, S[t][kb]);
;       }
;   }
	v_mfma_f32_32x32x16_bf16 v[112:127], v[144:147], v[188:191], v[112:127]
	ds_read_b128 v[144:147], v248 offset:1024
	s_waitcnt lgkmcnt(3)
	v_mfma_f32_32x32x16_bf16 v[96:111], v[148:151], v[188:191], v[96:111]
	ds_read_b128 v[148:151], v248 offset:9216
	s_waitcnt lgkmcnt(3)
	v_mfma_f32_32x32x16_bf16 v[80:95], v[152:155], v[188:191], v[80:95]
	ds_read_b128 v[152:155], v248 offset:33792
	s_waitcnt lgkmcnt(3)
	v_mfma_f32_32x32x16_bf16 v[64:79], v[156:159], v[188:191], v[64:79]
	ds_read_b128 v[156:159], v248 offset:41984
	s_waitcnt lgkmcnt(3)
	v_mfma_f32_32x32x16_bf16 v[48:63], v[144:147], v[188:191], v[48:63]
	ds_read_b128 v[144:147], v133 offset:1024
	s_waitcnt lgkmcnt(3)
	v_mfma_f32_32x32x16_bf16 v[32:47], v[148:151], v[188:191], v[32:47]
	ds_read_b128 v[148:151], v133 offset:9216
	s_waitcnt lgkmcnt(3)
	v_mfma_f32_32x32x16_bf16 v[16:31], v[152:155], v[188:191], v[16:31]
	ds_read_b128 v[152:155], v133 offset:33792
	s_waitcnt lgkmcnt(3)
	v_mfma_f32_32x32x16_bf16 v[0:15], v[156:159], v[188:191], v[0:15]
	ds_read_b128 v[156:159], v133 offset:41984
	s_waitcnt vmcnt(10) lgkmcnt(3)
	v_mfma_f32_32x32x16_bf16 v[112:127], v[144:147], v[192:195], v[112:127]
	ds_read_b128 v[144:147], v249 offset:1024
	s_waitcnt lgkmcnt(3)
	v_mfma_f32_32x32x16_bf16 v[96:111], v[148:151], v[192:195], v[96:111]
	ds_read_b128 v[148:151], v249 offset:9216
	s_waitcnt lgkmcnt(3)
	v_mfma_f32_32x32x16_bf16 v[80:95], v[152:155], v[192:195], v[80:95]
	ds_read_b128 v[152:155], v249 offset:33792
	s_waitcnt lgkmcnt(3)
	v_mfma_f32_32x32x16_bf16 v[64:79], v[156:159], v[192:195], v[64:79]
	ds_read_b128 v[156:159], v249 offset:41984
	s_waitcnt lgkmcnt(3)
	v_mfma_f32_32x32x16_bf16 v[48:63], v[144:147], v[192:195], v[48:63]
	ds_read_b128 v[144:147], v129 offset:1536
	s_waitcnt lgkmcnt(3)
	v_mfma_f32_32x32x16_bf16 v[32:47], v[148:151], v[192:195], v[32:47]
	ds_read_b128 v[148:151], v129 offset:9728
	s_waitcnt lgkmcnt(3)
	v_mfma_f32_32x32x16_bf16 v[16:31], v[152:155], v[192:195], v[16:31]
	ds_read_b128 v[152:155], v129 offset:34304
	s_waitcnt lgkmcnt(3)
	v_mfma_f32_32x32x16_bf16 v[0:15], v[156:159], v[192:195], v[0:15]
	ds_read_b128 v[156:159], v129 offset:42496
	s_waitcnt vmcnt(9) lgkmcnt(3)
	v_mfma_f32_32x32x16_bf16 v[112:127], v[144:147], v[196:199], v[112:127]
	ds_read_b128 v[144:147], v248 offset:1536
	s_waitcnt lgkmcnt(3)
	v_mfma_f32_32x32x16_bf16 v[96:111], v[148:151], v[196:199], v[96:111]
	ds_read_b128 v[148:151], v248 offset:9728
	s_waitcnt lgkmcnt(3)
	v_mfma_f32_32x32x16_bf16 v[80:95], v[152:155], v[196:199], v[80:95]
	ds_read_b128 v[152:155], v248 offset:34304
	s_waitcnt lgkmcnt(3)
	v_mfma_f32_32x32x16_bf16 v[64:79], v[156:159], v[196:199], v[64:79]
	ds_read_b128 v[156:159], v248 offset:42496
	s_waitcnt lgkmcnt(3)
	v_mfma_f32_32x32x16_bf16 v[48:63], v[144:147], v[196:199], v[48:63]
	ds_read_b128 v[144:147], v133 offset:1536
	s_waitcnt lgkmcnt(3)
	v_mfma_f32_32x32x16_bf16 v[32:47], v[148:151], v[196:199], v[32:47]
	ds_read_b128 v[148:151], v133 offset:9728
	s_waitcnt lgkmcnt(3)
	v_mfma_f32_32x32x16_bf16 v[16:31], v[152:155], v[196:199], v[16:31]
	ds_read_b128 v[152:155], v133 offset:34304
	s_waitcnt lgkmcnt(3)
	v_mfma_f32_32x32x16_bf16 v[0:15], v[156:159], v[196:199], v[0:15]
	ds_read_b128 v[156:159], v133 offset:42496
	s_waitcnt vmcnt(8) lgkmcnt(3)
	v_mfma_f32_32x32x16_bf16 v[112:127], v[144:147], v[200:203], v[112:127]
	ds_read_b128 v[144:147], v249 offset:1536
	s_waitcnt lgkmcnt(3)
	v_mfma_f32_32x32x16_bf16 v[96:111], v[148:151], v[200:203], v[96:111]
	ds_read_b128 v[148:151], v249 offset:9728
	s_waitcnt lgkmcnt(3)
	v_mfma_f32_32x32x16_bf16 v[80:95], v[152:155], v[200:203], v[80:95]
	ds_read_b128 v[152:155], v249 offset:34304
	s_waitcnt lgkmcnt(3)
	v_mfma_f32_32x32x16_bf16 v[64:79], v[156:159], v[200:203], v[64:79]
	ds_read_b128 v[156:159], v249 offset:42496
	s_waitcnt lgkmcnt(3)
	v_mfma_f32_32x32x16_bf16 v[48:63], v[144:147], v[200:203], v[48:63]
	ds_read_b128 v[144:147], v129 offset:16384
	s_waitcnt lgkmcnt(3)
	v_mfma_f32_32x32x16_bf16 v[32:47], v[148:151], v[200:203], v[32:47]
	ds_read_b128 v[148:151], v129 offset:24576
	s_waitcnt lgkmcnt(3)
	v_mfma_f32_32x32x16_bf16 v[16:31], v[152:155], v[200:203], v[16:31]
	ds_read_b128 v[152:155], v129 offset:49152
	s_waitcnt lgkmcnt(3)
	v_mfma_f32_32x32x16_bf16 v[0:15], v[156:159], v[200:203], v[0:15]
	ds_read_b128 v[156:159], v129 offset:57344
	s_waitcnt vmcnt(7) lgkmcnt(3)
	v_mfma_f32_32x32x16_bf16 v[112:127], v[144:147], v[204:207], v[112:127]
	ds_read_b128 v[144:147], v248 offset:16384
	s_waitcnt lgkmcnt(3)
	v_mfma_f32_32x32x16_bf16 v[96:111], v[148:151], v[204:207], v[96:111]
	ds_read_b128 v[148:151], v248 offset:24576
	s_waitcnt lgkmcnt(3)
	v_mfma_f32_32x32x16_bf16 v[80:95], v[152:155], v[204:207], v[80:95]
	ds_read_b128 v[152:155], v248 offset:49152
	s_waitcnt lgkmcnt(3)
	v_mfma_f32_32x32x16_bf16 v[64:79], v[156:159], v[204:207], v[64:79]
	ds_read_b128 v[156:159], v248 offset:57344
	s_waitcnt lgkmcnt(3)
	v_mfma_f32_32x32x16_bf16 v[48:63], v[144:147], v[204:207], v[48:63]
	ds_read_b128 v[144:147], v133 offset:16384
	s_waitcnt lgkmcnt(3)
	v_mfma_f32_32x32x16_bf16 v[32:47], v[148:151], v[204:207], v[32:47]
	ds_read_b128 v[148:151], v133 offset:24576
	s_waitcnt lgkmcnt(3)
	v_mfma_f32_32x32x16_bf16 v[16:31], v[152:155], v[204:207], v[16:31]
	ds_read_b128 v[152:155], v133 offset:49152
	s_waitcnt lgkmcnt(3)
	v_mfma_f32_32x32x16_bf16 v[0:15], v[156:159], v[204:207], v[0:15]
	ds_read_b128 v[156:159], v133 offset:57344
	s_waitcnt vmcnt(6) lgkmcnt(3)
	v_mfma_f32_32x32x16_bf16 v[112:127], v[144:147], v[208:211], v[112:127]
	ds_read_b128 v[144:147], v249 offset:16384
	s_waitcnt lgkmcnt(3)
; #define LDSP(T, p) ((__attribute__((address_space(3))) T*)(p))
; #define MFMA32(a, b, c) __builtin_amdgcn_mfma_f32_32x32x16_bf16((a), (b), (c), 0, 0, 0)
; DI void xattn_unit(const bf16_t* __restrict__ Qg, const bf16_t* __restrict__ Kg, const bf16_t* __restrict__ Vg, bf16_t* __restrict__ Og, lds_t* shm) {
;     ...
; #pragma unroll
;   for (int ss = 0; ss < 16; ++ss) {
;     const int cgl = 2 * ss, img = cgl >> 4;
;     const bf16x8 qv = gld<bf16x8>(Qg + 16 * ss, qoff);
; #pragma unroll
;     for (int t = 0; t < 4; ++t)
; #pragma unroll
;       for (int kb = 0; kb < 2; ++kb) {
;         const bf16x8 kf = *LDSP(const bf16x8, shm + t * 32768 + img * 16384 + kb * 8192 + 512 * ((cgl & 15) >> 2) + ((cgl & 2) ? ka2 : ka0));
;         S[t][kb] = MFMA32(kf, qv, S[t][kb]);
;       }
;   }
	v_mfma_f32_32x32x16_bf16 v[96:111], v[148:151], v[208:211], v[96:111]
	ds_read_b128 v[148:151], v249 offset:24576
	s_waitcnt lgkmcnt(3)
	v_mfma_f32_32x32x16_bf16 v[80:95], v[152:155], v[208:211], v[80:95]
	ds_read_b128 v[152:155], v249 offset:49152
	s_waitcnt lgkmcnt(3)
	v_mfma_f32_32x32x16_bf16 v[64:79], v[156:159], v[208:211], v[64:79]
	ds_read_b128 v[156:159], v249 offset:57344
	s_waitcnt lgkmcnt(3)
	v_mfma_f32_32x32x16_bf16 v[48:63], v[144:147], v[208:211], v[48:63]
	ds_read_b128 v[144:147], v129 offset:16896
	s_waitcnt lgkmcnt(3)
	v_mfma_f32_32x32x16_bf16 v[32:47], v[148:151], v[208:211], v[32:47]
	ds_read_b128 v[148:151], v129 offset:25088
	s_waitcnt lgkmcnt(3)
	v_mfma_f32_32x32x16_bf16 v[16:31], v[152:155], v[208:211], v[16:31]
	ds_read_b128 v[152:155], v129 offset:49664
	s_waitcnt lgkmcnt(3)
	v_mfma_f32_32x32x16_bf16 v[0:15], v[156:159], v[208:211], v[0:15]
	ds_read_b128 v[156:159], v129 offset:57856
	s_waitcnt vmcnt(5) lgkmcnt(3)
	v_mfma_f32_32x32x16_bf16 v[112:127], v[144:147], v[216:219], v[112:127]
	ds_read_b128 v[144:147], v248 offset:16896
	s_waitcnt lgkmcnt(3)
	v_mfma_f32_32x32x16_bf16 v[96:111], v[148:151], v[216:219], v[96:111]
	ds_read_b128 v[148:151], v248 offset:25088
	s_waitcnt lgkmcnt(3)
	v_mfma_f32_32x32x16_bf16 v[80:95], v[152:155], v[216:219], v[80:95]
	ds_read_b128 v[152:155], v248 offset:49664
	s_waitcnt lgkmcnt(3)
	v_mfma_f32_32x32x16_bf16 v[64:79], v[156:159], v[216:219], v[64:79]
	ds_read_b128 v[156:159], v248 offset:57856
	s_waitcnt lgkmcnt(3)
	v_mfma_f32_32x32x16_bf16 v[48:63], v[144:147], v[216:219], v[48:63]
	ds_read_b128 v[144:147], v133 offset:16896
	s_waitcnt lgkmcnt(3)
	v_mfma_f32_32x32x16_bf16 v[32:47], v[148:151], v[216:219], v[32:47]
	ds_read_b128 v[148:151], v133 offset:25088
	s_waitcnt lgkmcnt(3)
	v_mfma_f32_32x32x16_bf16 v[16:31], v[152:155], v[216:219], v[16:31]
	ds_read_b128 v[152:155], v133 offset:49664
	s_waitcnt lgkmcnt(3)
	v_mfma_f32_32x32x16_bf16 v[0:15], v[156:159], v[216:219], v[0:15]
	ds_read_b128 v[156:159], v133 offset:57856
	s_waitcnt vmcnt(4) lgkmcnt(3)
	v_mfma_f32_32x32x16_bf16 v[112:127], v[144:147], v[220:223], v[112:127]
	ds_read_b128 v[144:147], v249 offset:16896
	s_waitcnt lgkmcnt(3)
	v_mfma_f32_32x32x16_bf16 v[96:111], v[148:151], v[220:223], v[96:111]
	ds_read_b128 v[148:151], v249 offset:25088
	s_waitcnt lgkmcnt(3)
	v_mfma_f32_32x32x16_bf16 v[80:95], v[152:155], v[220:223], v[80:95]
	ds_read_b128 v[152:155], v249 offset:49664
	s_waitcnt lgkmcnt(3)
	v_mfma_f32_32x32x16_bf16 v[64:79], v[156:159], v[220:223], v[64:79]
	ds_read_b128 v[156:159], v249 offset:57856
	s_waitcnt lgkmcnt(3)
	v_mfma_f32_32x32x16_bf16 v[48:63], v[144:147], v[220:223], v[48:63]
	ds_read_b128 v[144:147], v129 offset:17408
	s_waitcnt lgkmcnt(3)
	v_mfma_f32_32x32x16_bf16 v[32:47], v[148:151], v[220:223], v[32:47]
	ds_read_b128 v[148:151], v129 offset:25600
	s_waitcnt lgkmcnt(3)
	v_mfma_f32_32x32x16_bf16 v[16:31], v[152:155], v[220:223], v[16:31]
	ds_read_b128 v[152:155], v129 offset:50176
	s_waitcnt lgkmcnt(3)
	v_mfma_f32_32x32x16_bf16 v[0:15], v[156:159], v[220:223], v[0:15]
	ds_read_b128 v[156:159], v129 offset:58368
	s_waitcnt vmcnt(3) lgkmcnt(3)
	v_mfma_f32_32x32x16_bf16 v[112:127], v[144:147], v[224:227], v[112:127]
	ds_read_b128 v[144:147], v248 offset:17408
	s_waitcnt lgkmcnt(3)
	v_mfma_f32_32x32x16_bf16 v[96:111], v[148:151], v[224:227], v[96:111]
	ds_read_b128 v[148:151], v248 offset:25600
	s_waitcnt lgkmcnt(3)
	v_mfma_f32_32x32x16_bf16 v[80:95], v[152:155], v[224:227], v[80:95]
	ds_read_b128 v[152:155], v248 offset:50176
	s_waitcnt lgkmcnt(3)
	v_mfma_f32_32x32x16_bf16 v[64:79], v[156:159], v[224:227], v[64:79]
	ds_read_b128 v[156:159], v248 offset:58368
	s_waitcnt lgkmcnt(3)
	v_mfma_f32_32x32x16_bf16 v[48:63], v[144:147], v[224:227], v[48:63]
	ds_read_b128 v[144:147], v133 offset:17408
	s_waitcnt lgkmcnt(3)
	v_mfma_f32_32x32x16_bf16 v[32:47], v[148:151], v[224:227], v[32:47]
	ds_read_b128 v[148:151], v133 offset:25600
	s_waitcnt lgkmcnt(3)
	v_mfma_f32_32x32x16_bf16 v[16:31], v[152:155], v[224:227], v[16:31]
	ds_read_b128 v[152:155], v133 offset:50176
	s_waitcnt lgkmcnt(3)
	v_mfma_f32_32x32x16_bf16 v[0:15], v[156:159], v[224:227], v[0:15]
	ds_read_b128 v[156:159], v133 offset:58368
	s_waitcnt vmcnt(2) lgkmcnt(3)
	v_mfma_f32_32x32x16_bf16 v[112:127], v[144:147], v[228:231], v[112:127]
	ds_read_b128 v[144:147], v249 offset:17408
	s_waitcnt lgkmcnt(3)
	v_mfma_f32_32x32x16_bf16 v[96:111], v[148:151], v[228:231], v[96:111]
	ds_read_b128 v[148:151], v249 offset:25600
	s_waitcnt lgkmcnt(3)
	v_mfma_f32_32x32x16_bf16 v[80:95], v[152:155], v[228:231], v[80:95]
	ds_read_b128 v[152:155], v249 offset:50176
	s_waitcnt lgkmcnt(3)
	v_mfma_f32_32x32x16_bf16 v[64:79], v[156:159], v[228:231], v[64:79]
	ds_read_b128 v[156:159], v249 offset:58368
	s_waitcnt lgkmcnt(3)
	v_mfma_f32_32x32x16_bf16 v[48:63], v[144:147], v[228:231], v[48:63]
	ds_read_b128 v[144:147], v129 offset:17920
	s_waitcnt lgkmcnt(3)
	v_mfma_f32_32x32x16_bf16 v[32:47], v[148:151], v[228:231], v[32:47]
	ds_read_b128 v[148:151], v129 offset:26112
	s_waitcnt lgkmcnt(3)
	v_mfma_f32_32x32x16_bf16 v[16:31], v[152:155], v[228:231], v[16:31]
	ds_read_b128 v[152:155], v129 offset:50688
	s_waitcnt lgkmcnt(3)
	v_mfma_f32_32x32x16_bf16 v[0:15], v[156:159], v[228:231], v[0:15]
	ds_read_b128 v[156:159], v129 offset:58880
	s_waitcnt vmcnt(1) lgkmcnt(3)
	v_mfma_f32_32x32x16_bf16 v[112:127], v[144:147], v[232:235], v[112:127]
	ds_read_b128 v[144:147], v248 offset:17920
	s_waitcnt lgkmcnt(3)
	v_mfma_f32_32x32x16_bf16 v[96:111], v[148:151], v[232:235], v[96:111]
	ds_read_b128 v[148:151], v248 offset:26112
	s_waitcnt lgkmcnt(3)
; #define LDSP(T, p) ((__attribute__((address_space(3))) T*)(p))
; DI unsigned pk2(float lo, float hi) { bf2_t v = __builtin_convertvector((f32x2){lo, hi}, bf2_t); return __builtin_bit_cast(unsigned, v); }
; #define MFMA32(a, b, c) __builtin_amdgcn_mfma_f32_32x32x16_bf16((a), (b), (c), 0, 0, 0)
; DI void xattn_unit(const bf16_t* __restrict__ Qg, const bf16_t* __restrict__ Kg, const bf16_t* __restrict__ Vg, bf16_t* __restrict__ Og, lds_t* shm) {
;     ...
;   for (int ss = 0; ss < 16; ++ss) {
;     const int cgl = 2 * ss, img = cgl >> 4;
;     const bf16x8 qv = gld<bf16x8>(Qg + 16 * ss, qoff);
; #pragma unroll
;     for (int t = 0; t < 4; ++t)
; #pragma unroll
;       for (int kb = 0; kb < 2; ++kb) {
;         const bf16x8 kf = *LDSP(const bf16x8, shm + t * 32768 + img * 16384 + kb * 8192 + 512 * ((cgl & 15) >> 2) + ((cgl & 2) ? ka2 : ka0));
;         S[t][kb] = MFMA32(kf, qv, S[t][kb]);
;       }
;   }
;   float mx = S[0][0][0];
; #pragma unroll
;   for (int t = 0; t < 4; ++t)
; #pragma unroll
;     for (int kb = 0; kb < 2; ++kb)
; #pragma unroll
;       for (int i = 0; i < 16; ++i) mx = fmaxf(mx, S[t][kb][i]);
;   { const auto sw = __builtin_amdgcn_permlane32_swap(__float_as_uint(mx), __float_as_uint(mx), false, false); mx = fmaxf(__uint_as_float(sw[0]), __uint_as_float(sw[1])); }
;   float rs = 0.f;
;   bf16x8 P[4][2][2];
; #pragma unroll
;   for (int t = 0; t < 4; ++t)
; #pragma unroll
;     for (int kb = 0; kb < 2; ++kb)
; #pragma unroll
;       for (int s2 = 0; s2 < 2; ++s2) {
;         float e[8];
; #pragma unroll
;         for (int j = 0; j < 8; ++j) { e[j] = __builtin_amdgcn_exp2f(S[t][kb][8 * s2 + j] - mx); rs += e[j]; }
;         u32x4 w; w.x = pk2(e[0], e[1]); w.y = pk2(e[2], e[3]); w.z = pk2(e[4], e[5]); w.w = pk2(e[6], e[7]);
;         P[t][kb][s2] = __builtin_bit_cast(bf16x8, w);
;       }
	v_mfma_f32_32x32x16_bf16 v[80:95], v[152:155], v[232:235], v[80:95]
	ds_read_b128 v[152:155], v248 offset:50688
	s_waitcnt lgkmcnt(3)
	v_mfma_f32_32x32x16_bf16 v[64:79], v[156:159], v[232:235], v[64:79]
	ds_read_b128 v[156:159], v248 offset:58880
	s_waitcnt lgkmcnt(3)
	v_mfma_f32_32x32x16_bf16 v[48:63], v[144:147], v[232:235], v[48:63]
	ds_read_b128 v[144:147], v133 offset:17920
	s_waitcnt lgkmcnt(3)
	v_mfma_f32_32x32x16_bf16 v[32:47], v[148:151], v[232:235], v[32:47]
	ds_read_b128 v[148:151], v133 offset:26112
	s_waitcnt lgkmcnt(3)
	v_mfma_f32_32x32x16_bf16 v[16:31], v[152:155], v[232:235], v[16:31]
	ds_read_b128 v[152:155], v133 offset:50688
	s_waitcnt lgkmcnt(3)
	v_mfma_f32_32x32x16_bf16 v[0:15], v[156:159], v[232:235], v[0:15]
	ds_read_b128 v[156:159], v133 offset:58880
	s_waitcnt vmcnt(0) lgkmcnt(3)
	v_mfma_f32_32x32x16_bf16 v[112:127], v[144:147], v[236:239], v[112:127]
	ds_read_b128 v[144:147], v249 offset:17920
	s_waitcnt lgkmcnt(3)
	v_mfma_f32_32x32x16_bf16 v[96:111], v[148:151], v[236:239], v[96:111]
	ds_read_b128 v[148:151], v249 offset:26112
	s_waitcnt lgkmcnt(3)
	v_mfma_f32_32x32x16_bf16 v[80:95], v[152:155], v[236:239], v[80:95]
	ds_read_b128 v[152:155], v249 offset:50688
	s_waitcnt lgkmcnt(3)
	v_mfma_f32_32x32x16_bf16 v[64:79], v[156:159], v[236:239], v[64:79]
	ds_read_b128 v[156:159], v249 offset:58880
	s_waitcnt lgkmcnt(3)
	v_mfma_f32_32x32x16_bf16 v[48:63], v[144:147], v[236:239], v[48:63]
	s_waitcnt lgkmcnt(2)
	v_mfma_f32_32x32x16_bf16 v[32:47], v[148:151], v[236:239], v[32:47]
	s_waitcnt lgkmcnt(1)
	v_mfma_f32_32x32x16_bf16 v[16:31], v[152:155], v[236:239], v[16:31]
	s_waitcnt lgkmcnt(0)
	v_mfma_f32_32x32x16_bf16 v[0:15], v[156:159], v[236:239], v[0:15]
	v_max_f32_e32 v128, v113, v113
	v_max_f32_e32 v129, v112, v112
	v_max_f32_e32 v128, v129, v128
	v_max3_f32 v128, v128, v114, v115
	v_max3_f32 v128, v128, v116, v117
	v_max3_f32 v128, v128, v118, v119
	v_max3_f32 v128, v128, v120, v121
	v_max3_f32 v128, v128, v122, v123
	v_max3_f32 v128, v128, v124, v125
	v_max3_f32 v128, v128, v126, v127
	v_max3_f32 v128, v128, v96, v97
	v_max3_f32 v128, v128, v98, v99
	v_max3_f32 v128, v128, v100, v101
	v_max3_f32 v128, v128, v102, v103
	v_max3_f32 v128, v128, v104, v105
	v_max3_f32 v128, v128, v106, v107
	v_max3_f32 v128, v128, v108, v109
	v_max3_f32 v128, v128, v110, v111
	v_max3_f32 v128, v128, v80, v81
	v_max3_f32 v128, v128, v82, v83
	v_max3_f32 v128, v128, v84, v85
	v_max3_f32 v128, v128, v86, v87
	v_max3_f32 v128, v128, v88, v89
	v_max3_f32 v128, v128, v90, v91
	v_max3_f32 v128, v128, v92, v93
	v_max3_f32 v128, v128, v94, v95
	v_max3_f32 v128, v128, v64, v65
	v_max3_f32 v128, v128, v66, v67
	v_max3_f32 v128, v128, v68, v69
	v_max3_f32 v128, v128, v70, v71
	v_max3_f32 v128, v128, v72, v73
	v_max3_f32 v128, v128, v74, v75
	v_max3_f32 v128, v128, v76, v77
	v_max3_f32 v128, v128, v78, v79
	v_max3_f32 v128, v128, v48, v49
	v_max3_f32 v128, v128, v50, v51
	v_max3_f32 v128, v128, v52, v53
	v_max3_f32 v128, v128, v54, v55
	v_max3_f32 v128, v128, v56, v57
	v_max3_f32 v128, v128, v58, v59
	v_max3_f32 v128, v128, v60, v61
	v_max3_f32 v128, v128, v62, v63
	v_max3_f32 v128, v128, v32, v33
	v_max3_f32 v128, v128, v34, v35
	v_max3_f32 v128, v128, v36, v37
	v_max3_f32 v128, v128, v38, v39
	v_max3_f32 v128, v128, v40, v41
	v_max3_f32 v128, v128, v42, v43
	v_max3_f32 v128, v128, v44, v45
	v_max3_f32 v128, v128, v46, v47
	v_max3_f32 v128, v128, v16, v17
	v_max3_f32 v128, v128, v18, v19
	v_max3_f32 v128, v128, v20, v21
	v_max3_f32 v128, v128, v22, v23
	v_max3_f32 v128, v128, v24, v25
	v_max3_f32 v128, v128, v26, v27
	v_max3_f32 v128, v128, v28, v29
	v_max3_f32 v128, v128, v30, v31
	v_max3_f32 v128, v128, v0, v1
	v_max3_f32 v128, v128, v2, v3
	v_max3_f32 v128, v128, v4, v5
	v_max3_f32 v128, v128, v6, v7
	v_max3_f32 v128, v128, v8, v9
	v_max3_f32 v128, v128, v10, v11
	v_max3_f32 v128, v128, v12, v13
	v_max3_f32 v128, v128, v14, v15
	v_mov_b32_e32 v129, v128
	s_nop 1
	v_permlane32_swap_b32_e32 v128, v129
	v_max_f32_e32 v129, v129, v129
	v_max_f32_e32 v128, v128, v128
	v_max_f32_e32 v167, v128, v129
	v_sub_f32_e32 v112, v112, v167
	v_exp_f32_e32 v112, v112
	v_sub_f32_e32 v113, v113, v167
	v_exp_f32_e32 v113, v113
	v_sub_f32_e32 v114, v114, v167
	v_exp_f32_e32 v114, v114
	v_sub_f32_e32 v115, v115, v167
	v_exp_f32_e32 v227, v115
	v_sub_f32_e32 v115, v116, v167
	v_add_f32_e32 v128, 0, v112
	v_exp_f32_e32 v115, v115
	v_sub_f32_e32 v116, v117, v167
	v_add_f32_e32 v128, v113, v128
	v_exp_f32_e32 v116, v116
	v_sub_f32_e32 v117, v118, v167
	v_add_f32_e32 v128, v114, v128
	v_exp_f32_e32 v117, v117
	v_sub_f32_e32 v118, v119, v167
	v_add_f32_e32 v128, v227, v128
	v_exp_f32_e32 v118, v118
	v_sub_f32_e32 v120, v120, v167
	v_add_f32_e32 v128, v115, v128
	v_exp_f32_e32 v217, v120
	v_sub_f32_e32 v120, v121, v167
	v_add_f32_e32 v128, v116, v128
	v_exp_f32_e32 v221, v120
	v_sub_f32_e32 v120, v122, v167
	v_add_f32_e32 v128, v117, v128
	v_exp_f32_e32 v210, v120
	v_sub_f32_e32 v120, v123, v167
	v_add_f32_e32 v119, v118, v128
	v_exp_f32_e32 v218, v120
	v_sub_f32_e32 v120, v124, v167
	v_add_f32_e32 v119, v217, v119
	v_exp_f32_e32 v215, v120
	v_sub_f32_e32 v120, v125, v167
	v_add_f32_e32 v119, v221, v119
	v_exp_f32_e32 v220, v120
	v_sub_f32_e32 v120, v126, v167
	v_add_f32_e32 v119, v210, v119
	v_exp_f32_e32 v208, v120
	v_sub_f32_e32 v120, v127, v167
	v_add_f32_e32 v119, v218, v119
	v_exp_f32_e32 v216, v120
	v_sub_f32_e32 v96, v96, v167
	v_add_f32_e32 v119, v215, v119
	v_exp_f32_e32 v197, v96
	v_sub_f32_e32 v97, v97, v167
	v_add_f32_e32 v119, v220, v119
	v_exp_f32_e32 v201, v97
	v_sub_f32_e32 v97, v98, v167
	v_add_f32_e32 v119, v208, v119
	v_exp_f32_e32 v194, v97
; DI unsigned pk2(float lo, float hi) { bf2_t v = __builtin_convertvector((f32x2){lo, hi}, bf2_t); return __builtin_bit_cast(unsigned, v); }
; DI void xattn_unit(const bf16_t* __restrict__ Qg, const bf16_t* __restrict__ Kg, const bf16_t* __restrict__ Vg, bf16_t* __restrict__ Og, lds_t* shm) {
;     ...
;   float rs = 0.f;
;   bf16x8 P[4][2][2];
; #pragma unroll
;   for (int t = 0; t < 4; ++t)
; #pragma unroll
;     for (int kb = 0; kb < 2; ++kb)
; #pragma unroll
;       for (int s2 = 0; s2 < 2; ++s2) {
;         float e[8];
; #pragma unroll
;         for (int j = 0; j < 8; ++j) { e[j] = __builtin_amdgcn_exp2f(S[t][kb][8 * s2 + j] - mx); rs += e[j]; }
;         u32x4 w; w.x = pk2(e[0], e[1]); w.y = pk2(e[2], e[3]); w.z = pk2(e[4], e[5]); w.w = pk2(e[6], e[7]);
;         P[t][kb][s2] = __builtin_bit_cast(bf16x8, w);
;       }
;   const float l = rs + __shfl_xor(rs, 32);
	v_sub_f32_e32 v97, v99, v167
	v_add_f32_e32 v119, v216, v119
	v_exp_f32_e32 v198, v97
	v_sub_f32_e32 v97, v100, v167
	v_add_f32_e32 v96, v197, v119
	v_exp_f32_e32 v195, v97
	v_sub_f32_e32 v97, v101, v167
	v_add_f32_e32 v96, v201, v96
	v_exp_f32_e32 v199, v97
	v_sub_f32_e32 v97, v102, v167
	v_add_f32_e32 v96, v194, v96
	v_exp_f32_e32 v191, v97
	v_sub_f32_e32 v97, v103, v167
	v_add_f32_e32 v96, v198, v96
	v_exp_f32_e32 v193, v97
	v_sub_f32_e32 v97, v104, v167
	v_add_f32_e32 v96, v195, v96
	v_exp_f32_e32 v179, v97
	v_sub_f32_e32 v97, v105, v167
	v_add_f32_e32 v96, v199, v96
	v_exp_f32_e32 v183, v97
	v_sub_f32_e32 v97, v106, v167
	v_add_f32_e32 v96, v191, v96
	v_exp_f32_e32 v177, v97
	v_sub_f32_e32 v97, v107, v167
	v_add_f32_e32 v96, v193, v96
	v_exp_f32_e32 v180, v97
	v_sub_f32_e32 v97, v108, v167
	v_add_f32_e32 v96, v179, v96
	v_exp_f32_e32 v178, v97
	v_sub_f32_e32 v97, v109, v167
	v_add_f32_e32 v96, v183, v96
	v_exp_f32_e32 v181, v97
	v_sub_f32_e32 v97, v110, v167
	v_add_f32_e32 v96, v177, v96
	v_exp_f32_e32 v174, v97
	v_sub_f32_e32 v97, v111, v167
	v_add_f32_e32 v96, v180, v96
	v_exp_f32_e32 v176, v97
	v_sub_f32_e32 v80, v80, v167
	v_add_f32_e32 v96, v178, v96
	v_exp_f32_e32 v80, v80
	v_sub_f32_e32 v81, v81, v167
	v_add_f32_e32 v96, v181, v96
	v_exp_f32_e32 v81, v81
	v_sub_f32_e32 v82, v82, v167
	v_add_f32_e32 v96, v174, v96
	v_exp_f32_e32 v82, v82
	v_sub_f32_e32 v83, v83, v167
	v_add_f32_e32 v96, v176, v96
	v_exp_f32_e32 v83, v83
	v_sub_f32_e32 v84, v84, v167
	v_add_f32_e32 v96, v80, v96
	v_exp_f32_e32 v84, v84
	v_sub_f32_e32 v85, v85, v167
	v_add_f32_e32 v96, v81, v96
	v_exp_f32_e32 v85, v85
	v_sub_f32_e32 v86, v86, v167
	v_add_f32_e32 v96, v82, v96
	v_exp_f32_e32 v86, v86
	v_sub_f32_e32 v87, v87, v167
	v_add_f32_e32 v96, v83, v96
	v_exp_f32_e32 v87, v87
	v_cvt_pk_bf16_f32 v128, v80, v81
	v_sub_f32_e32 v80, v88, v167
	v_add_f32_e32 v96, v84, v96
	v_cvt_pk_bf16_f32 v129, v82, v83
	v_exp_f32_e32 v80, v80
	v_sub_f32_e32 v82, v89, v167
	v_add_f32_e32 v96, v85, v96
	v_exp_f32_e32 v82, v82
	v_sub_f32_e32 v83, v90, v167
	v_add_f32_e32 v96, v86, v96
	v_cvt_pk_bf16_f32 v130, v84, v85
	v_exp_f32_e32 v83, v83
	v_sub_f32_e32 v84, v91, v167
	v_add_f32_e32 v96, v87, v96
	v_exp_f32_e32 v84, v84
	v_sub_f32_e32 v85, v92, v167
	v_cvt_pk_bf16_f32 v131, v86, v87
	v_add_f32_e32 v81, v80, v96
	v_exp_f32_e32 v85, v85
	v_sub_f32_e32 v86, v93, v167
	v_add_f32_e32 v81, v82, v81
	v_exp_f32_e32 v86, v86
	v_sub_f32_e32 v87, v94, v167
	v_add_f32_e32 v81, v83, v81
	v_exp_f32_e32 v87, v87
	v_sub_f32_e32 v88, v95, v167
	v_add_f32_e32 v81, v84, v81
	v_exp_f32_e32 v88, v88
	v_sub_f32_e32 v64, v64, v167
	v_add_f32_e32 v81, v85, v81
	v_exp_f32_e32 v64, v64
	v_sub_f32_e32 v65, v65, v167
	v_add_f32_e32 v81, v86, v81
	v_exp_f32_e32 v65, v65
	v_sub_f32_e32 v66, v66, v167
	v_add_f32_e32 v81, v87, v81
	v_exp_f32_e32 v66, v66
	v_sub_f32_e32 v67, v67, v167
	v_add_f32_e32 v81, v88, v81
	v_exp_f32_e32 v67, v67
	v_sub_f32_e32 v68, v68, v167
	v_cvt_pk_bf16_f32 v132, v80, v82
	v_add_f32_e32 v80, v64, v81
	v_exp_f32_e32 v68, v68
	v_sub_f32_e32 v69, v69, v167
	v_add_f32_e32 v80, v65, v80
	v_exp_f32_e32 v69, v69
	v_sub_f32_e32 v70, v70, v167
	v_add_f32_e32 v80, v66, v80
	v_exp_f32_e32 v70, v70
	v_sub_f32_e32 v71, v71, v167
	v_add_f32_e32 v80, v67, v80
	v_exp_f32_e32 v71, v71
	v_cvt_pk_bf16_f32 v136, v64, v65
	v_sub_f32_e32 v64, v72, v167
	v_add_f32_e32 v80, v68, v80
	v_cvt_pk_bf16_f32 v137, v66, v67
	v_exp_f32_e32 v64, v64
	v_sub_f32_e32 v66, v73, v167
	v_add_f32_e32 v80, v69, v80
	v_exp_f32_e32 v66, v66
	v_sub_f32_e32 v67, v74, v167
	v_add_f32_e32 v80, v70, v80
	v_cvt_pk_bf16_f32 v138, v68, v69
	v_exp_f32_e32 v67, v67
	v_sub_f32_e32 v68, v75, v167
	v_add_f32_e32 v80, v71, v80
	v_exp_f32_e32 v68, v68
	v_sub_f32_e32 v69, v76, v167
	v_cvt_pk_bf16_f32 v139, v70, v71
	v_add_f32_e32 v65, v64, v80
	v_exp_f32_e32 v69, v69
	v_sub_f32_e32 v70, v77, v167
	v_add_f32_e32 v65, v66, v65
	v_exp_f32_e32 v70, v70
	v_sub_f32_e32 v71, v78, v167
	v_add_f32_e32 v65, v67, v65
	v_exp_f32_e32 v71, v71
	v_sub_f32_e32 v72, v79, v167
	v_add_f32_e32 v65, v68, v65
	v_exp_f32_e32 v72, v72
	v_sub_f32_e32 v48, v48, v167
	v_add_f32_e32 v65, v69, v65
	v_exp_f32_e32 v48, v48
	v_sub_f32_e32 v49, v49, v167
	v_add_f32_e32 v65, v70, v65
	v_exp_f32_e32 v49, v49
	v_sub_f32_e32 v50, v50, v167
	v_add_f32_e32 v65, v71, v65
	v_exp_f32_e32 v50, v50
	v_sub_f32_e32 v51, v51, v167
	v_add_f32_e32 v65, v72, v65
	v_exp_f32_e32 v51, v51
	v_sub_f32_e32 v52, v52, v167
	v_cvt_pk_bf16_f32 v156, v64, v66
	v_add_f32_e32 v64, v48, v65
	v_exp_f32_e32 v52, v52
	v_sub_f32_e32 v53, v53, v167
	v_add_f32_e32 v64, v49, v64
	v_exp_f32_e32 v53, v53
	v_sub_f32_e32 v54, v54, v167
	v_add_f32_e32 v64, v50, v64
	v_exp_f32_e32 v54, v54
	v_sub_f32_e32 v55, v55, v167
	v_add_f32_e32 v64, v51, v64
	v_exp_f32_e32 v55, v55
	v_cvt_pk_bf16_f32 v152, v48, v49
	v_sub_f32_e32 v48, v56, v167
	v_add_f32_e32 v64, v52, v64
	v_cvt_pk_bf16_f32 v153, v50, v51
	v_exp_f32_e32 v48, v48
	v_sub_f32_e32 v50, v57, v167
	v_add_f32_e32 v64, v53, v64
	v_exp_f32_e32 v50, v50
	v_sub_f32_e32 v51, v58, v167
	v_add_f32_e32 v64, v54, v64
	v_cvt_pk_bf16_f32 v154, v52, v53
	v_exp_f32_e32 v51, v51
	v_sub_f32_e32 v52, v59, v167
	v_add_f32_e32 v64, v55, v64
	v_exp_f32_e32 v52, v52
	v_sub_f32_e32 v53, v60, v167
	v_cvt_pk_bf16_f32 v155, v54, v55
	v_add_f32_e32 v49, v48, v64
	v_exp_f32_e32 v53, v53
	v_sub_f32_e32 v54, v61, v167
	v_add_f32_e32 v49, v50, v49
	v_exp_f32_e32 v54, v54
	v_sub_f32_e32 v55, v62, v167
	v_add_f32_e32 v49, v51, v49
	v_exp_f32_e32 v55, v55
	v_sub_f32_e32 v56, v63, v167
	v_add_f32_e32 v49, v52, v49
	v_exp_f32_e32 v56, v56
	v_sub_f32_e32 v32, v32, v167
	v_add_f32_e32 v49, v53, v49
; DI unsigned pk2(float lo, float hi) { bf2_t v = __builtin_convertvector((f32x2){lo, hi}, bf2_t); return __builtin_bit_cast(unsigned, v); }
; DI void xattn_unit(const bf16_t* __restrict__ Qg, const bf16_t* __restrict__ Kg, const bf16_t* __restrict__ Vg, bf16_t* __restrict__ Og, lds_t* shm) {
;     ...
; #pragma unroll
;   for (int t = 0; t < 4; ++t)
; #pragma unroll
;     for (int kb = 0; kb < 2; ++kb)
; #pragma unroll
;       for (int s2 = 0; s2 < 2; ++s2) {
;         float e[8];
; #pragma unroll
;         for (int j = 0; j < 8; ++j) { e[j] = __builtin_amdgcn_exp2f(S[t][kb][8 * s2 + j] - mx); rs += e[j]; }
;         u32x4 w; w.x = pk2(e[0], e[1]); w.y = pk2(e[2], e[3]); w.z = pk2(e[4], e[5]); w.w = pk2(e[6], e[7]);
;         P[t][kb][s2] = __builtin_bit_cast(bf16x8, w);
;       }
;   const float l = rs + __shfl_xor(rs, 32);
;   __builtin_amdgcn_sched_barrier(0);
;   __syncthreads();
;   __builtin_amdgcn_sched_barrier(0);
	v_exp_f32_e32 v32, v32
	v_sub_f32_e32 v33, v33, v167
	v_add_f32_e32 v49, v54, v49
	v_exp_f32_e32 v33, v33
	v_sub_f32_e32 v34, v34, v167
	v_add_f32_e32 v49, v55, v49
	v_exp_f32_e32 v34, v34
	v_sub_f32_e32 v35, v35, v167
	v_add_f32_e32 v49, v56, v49
	v_exp_f32_e32 v35, v35
	v_sub_f32_e32 v36, v36, v167
	v_cvt_pk_bf16_f32 v148, v48, v50
	v_add_f32_e32 v48, v32, v49
	v_exp_f32_e32 v36, v36
	v_sub_f32_e32 v37, v37, v167
	v_add_f32_e32 v48, v33, v48
	v_exp_f32_e32 v37, v37
	v_sub_f32_e32 v38, v38, v167
	v_add_f32_e32 v48, v34, v48
	v_exp_f32_e32 v38, v38
	v_sub_f32_e32 v39, v39, v167
	v_add_f32_e32 v48, v35, v48
	v_exp_f32_e32 v39, v39
	v_cvt_pk_bf16_f32 v140, v32, v33
	v_sub_f32_e32 v32, v40, v167
	v_add_f32_e32 v48, v36, v48
	v_cvt_pk_bf16_f32 v141, v34, v35
	v_exp_f32_e32 v32, v32
	v_sub_f32_e32 v34, v41, v167
	v_add_f32_e32 v48, v37, v48
	v_exp_f32_e32 v34, v34
	v_sub_f32_e32 v35, v42, v167
	v_add_f32_e32 v48, v38, v48
	v_cvt_pk_bf16_f32 v142, v36, v37
	v_exp_f32_e32 v35, v35
	v_sub_f32_e32 v36, v43, v167
	v_add_f32_e32 v48, v39, v48
	v_exp_f32_e32 v36, v36
	v_sub_f32_e32 v37, v44, v167
	v_cvt_pk_bf16_f32 v143, v38, v39
	v_add_f32_e32 v33, v32, v48
	v_exp_f32_e32 v37, v37
	v_sub_f32_e32 v38, v45, v167
	v_add_f32_e32 v33, v34, v33
	v_exp_f32_e32 v38, v38
	v_sub_f32_e32 v39, v46, v167
	v_add_f32_e32 v33, v35, v33
	v_exp_f32_e32 v39, v39
	v_sub_f32_e32 v40, v47, v167
	v_add_f32_e32 v33, v36, v33
	v_exp_f32_e32 v40, v40
	v_sub_f32_e32 v16, v16, v167
	v_add_f32_e32 v33, v37, v33
	v_exp_f32_e32 v171, v16
	v_sub_f32_e32 v17, v17, v167
	v_add_f32_e32 v33, v38, v33
	v_exp_f32_e32 v172, v17
	v_sub_f32_e32 v17, v18, v167
	v_add_f32_e32 v33, v39, v33
	v_exp_f32_e32 v173, v17
	v_sub_f32_e32 v17, v19, v167
	v_add_f32_e32 v33, v40, v33
	v_exp_f32_e32 v175, v17
	v_sub_f32_e32 v17, v20, v167
	v_add_f32_e32 v16, v171, v33
	v_exp_f32_e32 v182, v17
	v_sub_f32_e32 v17, v21, v167
	v_add_f32_e32 v16, v172, v16
	v_exp_f32_e32 v184, v17
	v_sub_f32_e32 v17, v22, v167
	v_add_f32_e32 v16, v173, v16
	v_exp_f32_e32 v185, v17
	v_sub_f32_e32 v17, v23, v167
	v_add_f32_e32 v16, v175, v16
	v_exp_f32_e32 v186, v17
	v_sub_f32_e32 v17, v24, v167
	v_add_f32_e32 v16, v182, v16
	v_exp_f32_e32 v187, v17
	v_sub_f32_e32 v17, v25, v167
	v_add_f32_e32 v16, v184, v16
	v_exp_f32_e32 v188, v17
	v_sub_f32_e32 v17, v26, v167
	v_add_f32_e32 v16, v185, v16
	v_exp_f32_e32 v189, v17
	v_sub_f32_e32 v17, v27, v167
	v_add_f32_e32 v16, v186, v16
	v_exp_f32_e32 v190, v17
	v_sub_f32_e32 v17, v28, v167
	v_add_f32_e32 v16, v187, v16
	v_exp_f32_e32 v192, v17
	v_sub_f32_e32 v17, v29, v167
	v_add_f32_e32 v16, v188, v16
	v_exp_f32_e32 v196, v17
	v_sub_f32_e32 v17, v30, v167
	v_add_f32_e32 v16, v189, v16
	v_exp_f32_e32 v200, v17
	v_sub_f32_e32 v17, v31, v167
	v_add_f32_e32 v16, v190, v16
	v_exp_f32_e32 v202, v17
	v_sub_f32_e32 v0, v0, v167
	v_add_f32_e32 v16, v192, v16
	v_exp_f32_e32 v203, v0
	v_sub_f32_e32 v1, v1, v167
	v_add_f32_e32 v16, v196, v16
	v_exp_f32_e32 v204, v1
	v_sub_f32_e32 v1, v2, v167
	v_add_f32_e32 v16, v200, v16
	v_exp_f32_e32 v205, v1
	v_sub_f32_e32 v1, v3, v167
	v_add_f32_e32 v16, v202, v16
	v_exp_f32_e32 v206, v1
	v_sub_f32_e32 v1, v4, v167
	v_add_f32_e32 v0, v203, v16
	v_exp_f32_e32 v207, v1
	v_sub_f32_e32 v1, v5, v167
	v_add_f32_e32 v0, v204, v0
	v_exp_f32_e32 v209, v1
	v_sub_f32_e32 v1, v6, v167
	v_add_f32_e32 v0, v205, v0
	v_exp_f32_e32 v211, v1
	v_sub_f32_e32 v1, v7, v167
	v_add_f32_e32 v0, v206, v0
	v_exp_f32_e32 v219, v1
	v_sub_f32_e32 v1, v8, v167
	v_add_f32_e32 v0, v207, v0
	v_exp_f32_e32 v222, v1
	v_sub_f32_e32 v1, v9, v167
	v_add_f32_e32 v0, v209, v0
	v_exp_f32_e32 v223, v1
	v_sub_f32_e32 v1, v10, v167
	v_add_f32_e32 v0, v211, v0
	v_exp_f32_e32 v224, v1
	v_sub_f32_e32 v1, v11, v167
	v_add_f32_e32 v0, v219, v0
	v_exp_f32_e32 v225, v1
	v_sub_f32_e32 v1, v12, v167
	v_add_f32_e32 v0, v222, v0
	v_exp_f32_e32 v226, v1
	v_sub_f32_e32 v1, v13, v167
	v_add_f32_e32 v0, v223, v0
	v_exp_f32_e32 v228, v1
	v_sub_f32_e32 v1, v14, v167
	v_add_f32_e32 v0, v224, v0
	v_exp_f32_e32 v229, v1
	v_sub_f32_e32 v1, v15, v167
	v_add_f32_e32 v0, v225, v0
	v_exp_f32_e32 v230, v1
	v_add_f32_e32 v0, v226, v0
	v_add_f32_e32 v0, v228, v0
	v_add_f32_e32 v0, v229, v0
	v_add_f32_e32 v167, v230, v0
	v_cvt_pk_bf16_f32 v133, v83, v84
	v_cvt_pk_bf16_f32 v134, v85, v86
	v_cvt_pk_bf16_f32 v135, v87, v88
	v_cvt_pk_bf16_f32 v157, v67, v68
	v_cvt_pk_bf16_f32 v158, v69, v70
	v_cvt_pk_bf16_f32 v159, v71, v72
	v_cvt_pk_bf16_f32 v149, v51, v52
	v_cvt_pk_bf16_f32 v150, v53, v54
	v_cvt_pk_bf16_f32 v151, v55, v56
	v_cvt_pk_bf16_f32 v144, v32, v34
	v_cvt_pk_bf16_f32 v145, v35, v36
	v_cvt_pk_bf16_f32 v146, v37, v38
	v_cvt_pk_bf16_f32 v147, v39, v40
	ds_bpermute_b32 v168, v213, v167
	s_waitcnt lgkmcnt(0)
	s_barrier
; #define MFMA32(a, b, c) __builtin_amdgcn_mfma_f32_32x32x16_bf16((a), (b), (c), 0, 0, 0)
; DI void xattn_unit(const bf16_t* __restrict__ Qg, const bf16_t* __restrict__ Kg, const bf16_t* __restrict__ Vg, bf16_t* __restrict__ Og, lds_t* shm) {
;     ...
;   __builtin_amdgcn_sched_barrier(0);
;   __syncthreads();
;   __builtin_amdgcn_sched_barrier(0);
; #pragma unroll
;   for (int t = 1; t < 4; ++t) issue_tile(Vg, t, t * 32768);
;   f32x16 O[NC];
; #pragma unroll
;   for (int c = 0; c < NC; ++c)
; #pragma unroll
;     for (int i = 0; i < 16; ++i) O[c][i] = 0.f;
; #pragma unroll
;   for (int t = 0; t < 4; ++t) {
;     if (t == 1) { __builtin_amdgcn_sched_barrier(0); asm volatile("s_waitcnt vmcnt(0)" ::: "memory"); __syncthreads(); __builtin_amdgcn_sched_barrier(0); }
;     const unsigned vbase = (t == 0) ? 131072u : (unsigned)t * 32768u;
; #pragma unroll
;     for (int ks = 0; ks < 4; ++ks)
; #pragma unroll
;       for (int c = 0; c < NC; ++c) {
;         const unsigned vo = vbase + (c >> 2) * 16384 + 512 * (c & 3) + 4096 * ks;
;         const bf16x8 vf = tr_pair(shm + vo + va0, shm + vo + 2048 + va1);
;         O[c] = MFMA32(vf, P[t][ks >> 1][ks & 1], O[c]);
;       }
	s_add_u32 s38, s36, 0x40800
	s_mov_b32 m0, s67
	s_addc_u32 s39, s37, 0
	global_load_lds_dwordx4 v160, s[38:39]
	s_mov_b32 m0, s0
	v_add_u32_e32 v2, s14, v170
	global_load_lds_dwordx4 v162, s[38:39]
	s_add_u32 s38, s36, 0x40900
	s_addc_u32 s39, s37, 0
	s_mov_b32 m0, s1
	s_add_u32 s0, s36, 0x80800
	global_load_lds_dwordx4 v160, s[38:39]
	s_mov_b32 m0, vcc_lo
	s_addc_u32 s1, s37, 0
	global_load_lds_dwordx4 v162, s[38:39]
	s_mov_b32 m0, vcc_hi
	v_cvt_pk_bf16_f32 v0, v112, v113
	global_load_lds_dwordx4 v160, s[0:1]
	s_mov_b32 m0, s28
	v_cvt_pk_bf16_f32 v1, v114, v227
	global_load_lds_dwordx4 v162, s[0:1]
	s_add_u32 s0, s36, 0x80900
	s_addc_u32 s1, s37, 0
	s_mov_b32 m0, s29
	v_cvt_pk_bf16_f32 v232, v217, v221
	global_load_lds_dwordx4 v160, s[0:1]
	s_mov_b32 m0, s68
	v_cvt_pk_bf16_f32 v233, v210, v218
	global_load_lds_dwordx4 v162, s[0:1]
	s_add_u32 s0, s36, 0xc0800
	s_addc_u32 s1, s37, 0
	s_mov_b32 m0, s69
	v_cvt_pk_bf16_f32 v234, v215, v220
	global_load_lds_dwordx4 v160, s[0:1]
	s_mov_b32 m0, s76
	v_cvt_pk_bf16_f32 v235, v208, v216
	global_load_lds_dwordx4 v162, s[0:1]
	s_add_u32 s0, s36, 0xc0900
	s_addc_u32 s1, s37, 0
	s_mov_b32 m0, s77
	s_nop 0
	global_load_lds_dwordx4 v160, s[0:1]
	s_mov_b32 m0, s78
	v_and_b32_e32 v160, 8, v169
	global_load_lds_dwordx4 v162, s[0:1]
	v_readlane_b32 s0, v254, 14
	v_add3_u32 v2, v2, v166, v160
	s_nop 0
	v_add_u32_e32 v3, s0, v170
	v_add3_u32 v3, v3, v165, v160
	ds_read_b64_tr_b16 v[4:5], v2
	ds_read_b64_tr_b16 v[6:7], v3
	v_readlane_b32 s0, v254, 25
	v_cvt_pk_bf16_f32 v2, v115, v116
	v_cvt_pk_bf16_f32 v3, v117, v118
	v_add_u32_e32 v8, s0, v170
	v_readlane_b32 s0, v254, 26
	v_add3_u32 v8, v8, v166, v160
	s_waitcnt lgkmcnt(0)
	v_mfma_f32_32x32x16_bf16 v[112:127], v[4:7], v[0:3], 0
	v_add_u32_e32 v9, s0, v170
	v_readlane_b32 s0, v254, 27
	v_add3_u32 v10, v9, v165, v160
	ds_read_b64_tr_b16 v[8:9], v8
	ds_read_b64_tr_b16 v[10:11], v10
	v_add_u32_e32 v4, s0, v170
	v_readlane_b32 s0, v254, 28
	v_add3_u32 v4, v4, v166, v160
	s_waitcnt lgkmcnt(0)
	v_mfma_f32_32x32x16_bf16 v[96:111], v[8:11], v[0:3], 0
	v_add_u32_e32 v5, s0, v170
	v_add3_u32 v6, v5, v165, v160
	ds_read_b64_tr_b16 v[4:5], v4
	ds_read_b64_tr_b16 v[6:7], v6
	v_readlane_b32 s0, v254, 29
	s_nop 1
	v_add_u32_e32 v8, s0, v170
	v_readlane_b32 s0, v254, 30
	v_add3_u32 v8, v8, v166, v160
	s_waitcnt lgkmcnt(0)
	v_mfma_f32_32x32x16_bf16 v[80:95], v[4:7], v[0:3], 0
	v_add_u32_e32 v9, s0, v170
	v_readlane_b32 s0, v254, 31
	v_add3_u32 v10, v9, v165, v160
	ds_read_b64_tr_b16 v[8:9], v8
	ds_read_b64_tr_b16 v[10:11], v10
	v_add_u32_e32 v4, s0, v170
	v_readlane_b32 s0, v254, 32
	v_add3_u32 v4, v4, v166, v160
	s_waitcnt lgkmcnt(0)
	v_mfma_f32_32x32x16_bf16 v[64:79], v[8:11], v[0:3], 0
	v_add_u32_e32 v5, s0, v170
	v_add3_u32 v6, v5, v165, v160
	ds_read_b64_tr_b16 v[4:5], v4
	ds_read_b64_tr_b16 v[6:7], v6
	v_readlane_b32 s0, v254, 33
	s_nop 1
	v_add_u32_e32 v8, s0, v170
	v_readlane_b32 s0, v254, 34
	v_add3_u32 v8, v8, v166, v160
	s_waitcnt lgkmcnt(0)
	v_mfma_f32_32x32x16_bf16 v[48:63], v[4:7], v[0:3], 0
	v_add_u32_e32 v9, s0, v170
	v_readlane_b32 s0, v254, 35
	v_add3_u32 v10, v9, v165, v160
	ds_read_b64_tr_b16 v[8:9], v8
	ds_read_b64_tr_b16 v[10:11], v10
	v_add_u32_e32 v4, s0, v170
	v_readlane_b32 s0, v254, 36
	v_add3_u32 v4, v4, v166, v160
	s_waitcnt lgkmcnt(0)
	v_mfma_f32_32x32x16_bf16 v[32:47], v[8:11], v[0:3], 0
	v_add_u32_e32 v5, s0, v170
	v_add3_u32 v6, v5, v165, v160
	ds_read_b64_tr_b16 v[4:5], v4
	ds_read_b64_tr_b16 v[6:7], v6
	v_readlane_b32 s0, v254, 37
	s_nop 1
	v_add_u32_e32 v8, s0, v170
	v_readlane_b32 s0, v254, 38
	s_waitcnt lgkmcnt(0)
	v_mfma_f32_32x32x16_bf16 v[16:31], v[4:7], v[0:3], 0
	v_add3_u32 v8, v8, v166, v160
	v_add_u32_e32 v9, s0, v170
	v_readlane_b32 s0, v254, 39
	v_add3_u32 v10, v9, v165, v160
	ds_read_b64_tr_b16 v[8:9], v8
	ds_read_b64_tr_b16 v[10:11], v10
	v_add_u32_e32 v4, s0, v170
	v_readlane_b32 s0, v254, 40
	v_add3_u32 v4, v4, v166, v160
	s_nop 0
	v_add_u32_e32 v5, s0, v170
	v_readlane_b32 s0, v254, 41
	v_add3_u32 v5, v5, v165, v160
	ds_read_b64_tr_b16 v[236:237], v4
	ds_read_b64_tr_b16 v[238:239], v5
	v_add_u32_e32 v162, s0, v170
	v_readlane_b32 s0, v254, 42
	v_add3_u32 v162, v162, v166, v160
	s_waitcnt lgkmcnt(0)
	v_mfma_f32_32x32x16_bf16 v[112:127], v[236:239], v[232:235], v[112:127]
	v_add_u32_e32 v169, s0, v170
	v_add3_u32 v169, v169, v165, v160
	ds_read_b64_tr_b16 v[240:241], v162
	ds_read_b64_tr_b16 v[242:243], v169
	v_readlane_b32 s0, v254, 43
	s_nop 1
	v_add_u32_e32 v162, s0, v170
	v_readlane_b32 s0, v254, 44
	v_add3_u32 v162, v162, v166, v160
	s_waitcnt lgkmcnt(0)
	v_mfma_f32_32x32x16_bf16 v[96:111], v[240:243], v[232:235], v[96:111]
	v_add_u32_e32 v169, s0, v170
	v_readlane_b32 s0, v254, 45
	v_add3_u32 v169, v169, v165, v160
	ds_read_b64_tr_b16 v[236:237], v162
	ds_read_b64_tr_b16 v[238:239], v169
	v_add_u32_e32 v162, s0, v170
	v_readlane_b32 s0, v254, 46
	v_add3_u32 v162, v162, v166, v160
	s_waitcnt lgkmcnt(0)
	v_mfma_f32_32x32x16_bf16 v[80:95], v[236:239], v[232:235], v[80:95]
	v_add_u32_e32 v169, s0, v170
	v_add3_u32 v169, v169, v165, v160
	ds_read_b64_tr_b16 v[240:241], v162
	ds_read_b64_tr_b16 v[242:243], v169
	v_readlane_b32 s0, v254, 47
	s_nop 1
	v_add_u32_e32 v162, s0, v170
	v_readlane_b32 s0, v254, 48
	v_add3_u32 v162, v162, v166, v160
	s_waitcnt lgkmcnt(0)
	v_mfma_f32_32x32x16_bf16 v[64:79], v[240:243], v[232:235], v[64:79]
	v_add_u32_e32 v169, s0, v170
	v_readlane_b32 s0, v254, 49
	v_add3_u32 v169, v169, v165, v160
	ds_read_b64_tr_b16 v[236:237], v162
	ds_read_b64_tr_b16 v[238:239], v169
	v_add_u32_e32 v162, s0, v170
	v_readlane_b32 s0, v254, 50
	v_add3_u32 v162, v162, v166, v160
	v_mfma_f32_32x32x16_bf16 v[0:15], v[8:11], v[0:3], 0
	v_add_u32_e32 v169, s0, v170
	v_add3_u32 v169, v169, v165, v160
	ds_read_b64_tr_b16 v[240:241], v162
	ds_read_b64_tr_b16 v[242:243], v169
	v_readlane_b32 s0, v254, 51
	s_nop 1
	v_add_u32_e32 v162, s0, v170
	v_readlane_b32 s0, v254, 52
	v_add3_u32 v162, v162, v166, v160
	s_waitcnt lgkmcnt(0)
; #define MFMA32(a, b, c) __builtin_amdgcn_mfma_f32_32x32x16_bf16((a), (b), (c), 0, 0, 0)
; DI void xattn_unit(const bf16_t* __restrict__ Qg, const bf16_t* __restrict__ Kg, const bf16_t* __restrict__ Vg, bf16_t* __restrict__ Og, lds_t* shm) {
;     ...
; #pragma unroll
;   for (int t = 0; t < 4; ++t) {
;     if (t == 1) { __builtin_amdgcn_sched_barrier(0); asm volatile("s_waitcnt vmcnt(0)" ::: "memory"); __syncthreads(); __builtin_amdgcn_sched_barrier(0); }
;     const unsigned vbase = (t == 0) ? 131072u : (unsigned)t * 32768u;
; #pragma unroll
;     for (int ks = 0; ks < 4; ++ks)
; #pragma unroll
;       for (int c = 0; c < NC; ++c) {
;         const unsigned vo = vbase + (c >> 2) * 16384 + 512 * (c & 3) + 4096 * ks;
;         const bf16x8 vf = tr_pair(shm + vo + va0, shm + vo + 2048 + va1);
;         O[c] = MFMA32(vf, P[t][ks >> 1][ks & 1], O[c]);
;       }
	v_mfma_f32_32x32x16_bf16 v[32:47], v[240:243], v[232:235], v[32:47]
	v_add_u32_e32 v169, s0, v170
	v_readlane_b32 s0, v254, 53
	v_add3_u32 v169, v169, v165, v160
	ds_read_b64_tr_b16 v[244:245], v162
	ds_read_b64_tr_b16 v[246:247], v169
	v_add_u32_e32 v162, s0, v170
	v_readlane_b32 s0, v254, 54
	v_add3_u32 v162, v162, v166, v160
	s_waitcnt lgkmcnt(0)
	v_mfma_f32_32x32x16_bf16 v[16:31], v[244:247], v[232:235], v[16:31]
	v_add_u32_e32 v169, s0, v170
	v_add3_u32 v169, v169, v165, v160
	ds_read_b64_tr_b16 v[240:241], v162
	ds_read_b64_tr_b16 v[242:243], v169
	v_readlane_b32 s0, v254, 55
	s_nop 1
	v_add_u32_e32 v162, s0, v170
	v_readlane_b32 s0, v254, 56
	v_add3_u32 v162, v162, v166, v160
	v_mfma_f32_32x32x16_bf16 v[48:63], v[236:239], v[232:235], v[48:63]
	v_add_u32_e32 v169, s0, v170
	v_readlane_b32 s0, v254, 57
	v_add3_u32 v169, v169, v165, v160
	ds_read_b64_tr_b16 v[244:245], v162
	ds_read_b64_tr_b16 v[246:247], v169
	v_add_u32_e32 v162, s0, v170
	v_readlane_b32 s0, v254, 58
	v_add3_u32 v162, v162, v166, v160
	s_waitcnt lgkmcnt(0)
	v_mfma_f32_32x32x16_bf16 v[0:15], v[240:243], v[232:235], v[0:15]
	v_add_u32_e32 v169, s0, v170
	v_add3_u32 v169, v169, v165, v160
	ds_read_b64_tr_b16 v[232:233], v162
	ds_read_b64_tr_b16 v[234:235], v169
	v_readlane_b32 s0, v254, 59
	v_cvt_pk_bf16_f32 v236, v197, v201
	v_cvt_pk_bf16_f32 v237, v194, v198
	v_add_u32_e32 v162, s0, v170
	v_readlane_b32 s0, v254, 60
	v_cvt_pk_bf16_f32 v238, v195, v199
	v_cvt_pk_bf16_f32 v239, v191, v193
	v_add3_u32 v162, v162, v166, v160
	v_add_u32_e32 v169, s0, v170
	v_readlane_b32 s0, v254, 61
	s_waitcnt lgkmcnt(0)
	v_mfma_f32_32x32x16_bf16 v[96:111], v[232:235], v[236:239], v[96:111]
	v_add3_u32 v169, v169, v165, v160
	ds_read_b64_tr_b16 v[232:233], v162
	ds_read_b64_tr_b16 v[234:235], v169
	v_add_u32_e32 v162, s0, v170
	v_readlane_b32 s0, v254, 62
	v_add3_u32 v162, v162, v166, v160
	s_nop 0
	v_add_u32_e32 v169, s0, v170
	v_add3_u32 v169, v169, v165, v160
	ds_read_b64_tr_b16 v[240:241], v162
	ds_read_b64_tr_b16 v[242:243], v169
	v_readlane_b32 s0, v254, 63
	s_waitcnt lgkmcnt(0)
	v_mfma_f32_32x32x16_bf16 v[80:95], v[232:235], v[236:239], v[80:95]
	v_add_u32_e32 v162, s0, v170
	v_readlane_b32 s0, v255, 0
	v_add3_u32 v162, v162, v166, v160
	s_nop 0
	v_add_u32_e32 v169, s0, v170
	v_readlane_b32 s0, v255, 1
	v_add3_u32 v169, v169, v165, v160
	ds_read_b64_tr_b16 v[232:233], v162
	ds_read_b64_tr_b16 v[234:235], v169
	v_add_u32_e32 v162, s0, v170
	v_readlane_b32 s0, v255, 2
	v_add3_u32 v162, v162, v166, v160
	v_mfma_f32_32x32x16_bf16 v[64:79], v[240:243], v[236:239], v[64:79]
	v_add_u32_e32 v169, s0, v170
	v_add3_u32 v169, v169, v165, v160
	ds_read_b64_tr_b16 v[240:241], v162
	ds_read_b64_tr_b16 v[242:243], v169
	v_readlane_b32 s0, v255, 3
	s_nop 1
	v_add_u32_e32 v162, s0, v170
	v_readlane_b32 s0, v255, 4
	v_add3_u32 v162, v162, v166, v160
	v_mfma_f32_32x32x16_bf16 v[112:127], v[244:247], v[236:239], v[112:127]
	v_add_u32_e32 v169, s0, v170
	v_readlane_b32 s0, v255, 5
	v_add3_u32 v169, v169, v165, v160
	ds_read_b64_tr_b16 v[244:245], v162
	ds_read_b64_tr_b16 v[246:247], v169
	v_add_u32_e32 v162, s0, v170
	v_readlane_b32 s0, v255, 6
	v_add3_u32 v162, v162, v166, v160
	s_waitcnt lgkmcnt(0)
	v_mfma_f32_32x32x16_bf16 v[32:47], v[240:243], v[236:239], v[32:47]
	v_add_u32_e32 v169, s0, v170
	v_add3_u32 v169, v169, v165, v160
	ds_read_b64_tr_b16 v[240:241], v162
	ds_read_b64_tr_b16 v[242:243], v169
	v_readlane_b32 s0, v255, 7
	s_nop 1
	v_add_u32_e32 v162, s0, v170
	v_readlane_b32 s0, v255, 8
	v_add3_u32 v162, v162, v166, v160
	v_mfma_f32_32x32x16_bf16 v[48:63], v[232:235], v[236:239], v[48:63]
	v_add_u32_e32 v169, s0, v170
	v_readlane_b32 s0, v255, 9
	v_cvt_pk_bf16_f32 v232, v179, v183
	v_cvt_pk_bf16_f32 v233, v177, v180
	v_cvt_pk_bf16_f32 v234, v178, v181
	v_add3_u32 v169, v169, v165, v160
	ds_read_b64_tr_b16 v[178:179], v162
	ds_read_b64_tr_b16 v[180:181], v169
	v_add_u32_e32 v162, s0, v170
	v_readlane_b32 s0, v255, 10
	v_add3_u32 v162, v162, v166, v160
	v_mfma_f32_32x32x16_bf16 v[16:31], v[244:247], v[236:239], v[16:31]
	v_add_u32_e32 v169, s0, v170
	v_add3_u32 v169, v169, v165, v160
	v_readlane_b32 s0, v255, 11
	v_cvt_pk_bf16_f32 v235, v174, v176
	s_waitcnt lgkmcnt(0)
	v_mfma_f32_32x32x16_bf16 v[0:15], v[240:243], v[236:239], v[0:15]
	ds_read_b64_tr_b16 v[236:237], v162
	ds_read_b64_tr_b16 v[238:239], v169
	v_add_u32_e32 v162, s0, v170
	v_readlane_b32 s0, v255, 12
	v_add3_u32 v162, v162, v166, v160
	s_nop 0
	v_add_u32_e32 v169, s0, v170
	v_readlane_b32 s0, v255, 13
	v_mfma_f32_32x32x16_bf16 v[112:127], v[178:181], v[232:235], v[112:127]
	v_add3_u32 v169, v169, v165, v160
	ds_read_b64_tr_b16 v[176:177], v162
	ds_read_b64_tr_b16 v[178:179], v169
	v_add_u32_e32 v162, s0, v170
	v_readlane_b32 s0, v255, 14
	v_add3_u32 v162, v162, v166, v160
	s_nop 0
	v_add_u32_e32 v169, s0, v170
	s_waitcnt lgkmcnt(0)
	v_mfma_f32_32x32x16_bf16 v[96:111], v[236:239], v[232:235], v[96:111]
	v_add3_u32 v169, v169, v165, v160
	ds_read_b64_tr_b16 v[236:237], v162
	ds_read_b64_tr_b16 v[238:239], v169
	v_readlane_b32 s0, v255, 15
	s_nop 1
	v_add_u32_e32 v162, s0, v170
	v_readlane_b32 s0, v255, 16
	v_add3_u32 v162, v162, v166, v160
	v_mfma_f32_32x32x16_bf16 v[80:95], v[176:179], v[232:235], v[80:95]
	v_add_u32_e32 v169, s0, v170
	v_readlane_b32 s0, v255, 17
	v_add3_u32 v169, v169, v165, v160
	ds_read_b64_tr_b16 v[176:177], v162
	ds_read_b64_tr_b16 v[178:179], v169
	v_add_u32_e32 v162, s0, v170
	v_readlane_b32 s0, v255, 18
	v_add3_u32 v162, v162, v166, v160
	s_waitcnt lgkmcnt(0)
	v_mfma_f32_32x32x16_bf16 v[64:79], v[236:239], v[232:235], v[64:79]
	v_add_u32_e32 v169, s0, v170
	v_add3_u32 v169, v169, v165, v160
	ds_read_b64_tr_b16 v[236:237], v162
	ds_read_b64_tr_b16 v[238:239], v169
	v_readlane_b32 s0, v255, 19
	s_nop 1
	v_add_u32_e32 v162, s0, v170
	v_readlane_b32 s0, v255, 20
	v_add3_u32 v162, v162, v166, v160
	v_mfma_f32_32x32x16_bf16 v[48:63], v[176:179], v[232:235], v[48:63]
	v_add_u32_e32 v169, s0, v170
	v_readlane_b32 s0, v255, 21
	v_add3_u32 v169, v169, v165, v160
	ds_read_b64_tr_b16 v[176:177], v162
	ds_read_b64_tr_b16 v[178:179], v169
	v_add_u32_e32 v162, s0, v170
	v_readlane_b32 s0, v255, 22
	v_add3_u32 v162, v162, v166, v160
	s_waitcnt lgkmcnt(0)
	v_mfma_f32_32x32x16_bf16 v[32:47], v[236:239], v[232:235], v[32:47]
	v_add_u32_e32 v169, s0, v170
	v_add3_u32 v169, v169, v165, v160
	ds_read_b64_tr_b16 v[236:237], v162
	ds_read_b64_tr_b16 v[238:239], v169
	v_mfma_f32_32x32x16_bf16 v[16:31], v[176:179], v[232:235], v[16:31]
	s_waitcnt lgkmcnt(0)
	v_mfma_f32_32x32x16_bf16 v[0:15], v[236:239], v[232:235], v[0:15]
	s_waitcnt vmcnt(0)
	s_waitcnt vmcnt(0)
	s_barrier
; #define MFMA32(a, b, c) __builtin_amdgcn_mfma_f32_32x32x16_bf16((a), (b), (c), 0, 0, 0)
; DI void xattn_unit(const bf16_t* __restrict__ Qg, const bf16_t* __restrict__ Kg, const bf16_t* __restrict__ Vg, bf16_t* __restrict__ Og, lds_t* shm) {
;     ...
; #pragma unroll
;   for (int t = 0; t < 4; ++t) {
;     if (t == 1) { __builtin_amdgcn_sched_barrier(0); asm volatile("s_waitcnt vmcnt(0)" ::: "memory"); __syncthreads(); __builtin_amdgcn_sched_barrier(0); }
;     const unsigned vbase = (t == 0) ? 131072u : (unsigned)t * 32768u;
; #pragma unroll
;     for (int ks = 0; ks < 4; ++ks)
; #pragma unroll
;       for (int c = 0; c < NC; ++c) {
;         const unsigned vo = vbase + (c >> 2) * 16384 + 512 * (c & 3) + 4096 * ks;
;         const bf16x8 vf = tr_pair(shm + vo + va0, shm + vo + 2048 + va1);
;         O[c] = MFMA32(vf, P[t][ks >> 1][ks & 1], O[c]);
;       }
	v_add_u32_e32 v162, 0, v170
	v_add3_u32 v169, v162, v166, v160
	v_add3_u32 v162, v162, v165, v160
	ds_read_b64_tr_b16 v[232:233], v169 offset:32768
	ds_read_b64_tr_b16 v[234:235], v162 offset:34816
	s_add_i32 s0, 0, 0x10000
	s_add_i32 s2, s2, 1
	v_readlane_b32 s68, v254, 0
	s_nop 1
	ds_read_b64_tr_b16 v[236:237], v169 offset:33280
	ds_read_b64_tr_b16 v[238:239], v162 offset:35328
	ds_read_b64_tr_b16 v[240:241], v169 offset:33792
	ds_read_b64_tr_b16 v[242:243], v162 offset:35840
	s_waitcnt lgkmcnt(4)
	v_mfma_f32_32x32x16_bf16 v[112:127], v[232:235], v[128:131], v[112:127]
	ds_read_b64_tr_b16 v[232:233], v169 offset:34304
	ds_read_b64_tr_b16 v[234:235], v162 offset:36352
	s_waitcnt lgkmcnt(4)
	v_mfma_f32_32x32x16_bf16 v[96:111], v[236:239], v[128:131], v[96:111]
	ds_read_b64_tr_b16 v[236:237], v169 offset:49152
	ds_read_b64_tr_b16 v[238:239], v162 offset:51200
	s_waitcnt lgkmcnt(4)
	v_mfma_f32_32x32x16_bf16 v[80:95], v[240:243], v[128:131], v[80:95]
	ds_read_b64_tr_b16 v[240:241], v169 offset:49664
	ds_read_b64_tr_b16 v[242:243], v162 offset:51712
	s_waitcnt lgkmcnt(4)
	v_mfma_f32_32x32x16_bf16 v[64:79], v[232:235], v[128:131], v[64:79]
	ds_read_b64_tr_b16 v[232:233], v169 offset:50176
	ds_read_b64_tr_b16 v[234:235], v162 offset:52224
	s_waitcnt lgkmcnt(4)
	v_mfma_f32_32x32x16_bf16 v[48:63], v[236:239], v[128:131], v[48:63]
	ds_read_b64_tr_b16 v[236:237], v169 offset:50688
	ds_read_b64_tr_b16 v[238:239], v162 offset:52736
	s_waitcnt lgkmcnt(4)
	v_mfma_f32_32x32x16_bf16 v[32:47], v[240:243], v[128:131], v[32:47]
	ds_read_b64_tr_b16 v[240:241], v169 offset:36864
	ds_read_b64_tr_b16 v[242:243], v162 offset:38912
	s_waitcnt lgkmcnt(4)
	v_mfma_f32_32x32x16_bf16 v[16:31], v[232:235], v[128:131], v[16:31]
	ds_read_b64_tr_b16 v[232:233], v169 offset:37376
	ds_read_b64_tr_b16 v[234:235], v162 offset:39424
	s_waitcnt lgkmcnt(4)
	v_mfma_f32_32x32x16_bf16 v[0:15], v[236:239], v[128:131], v[0:15]
	ds_read_b64_tr_b16 v[236:237], v169 offset:37888
	ds_read_b64_tr_b16 v[238:239], v162 offset:39936
	s_waitcnt lgkmcnt(4)
	v_mfma_f32_32x32x16_bf16 v[112:127], v[240:243], v[132:135], v[112:127]
	ds_read_b64_tr_b16 v[240:241], v169 offset:38400
	ds_read_b64_tr_b16 v[242:243], v162 offset:40448
	s_waitcnt lgkmcnt(4)
	v_mfma_f32_32x32x16_bf16 v[96:111], v[232:235], v[132:135], v[96:111]
	ds_read_b64_tr_b16 v[232:233], v169 offset:53248
	ds_read_b64_tr_b16 v[234:235], v162 offset:55296
	s_waitcnt lgkmcnt(4)
	v_mfma_f32_32x32x16_bf16 v[80:95], v[236:239], v[132:135], v[80:95]
	ds_read_b64_tr_b16 v[236:237], v169 offset:53760
	ds_read_b64_tr_b16 v[238:239], v162 offset:55808
	s_waitcnt lgkmcnt(4)
	v_mfma_f32_32x32x16_bf16 v[64:79], v[240:243], v[132:135], v[64:79]
	ds_read_b64_tr_b16 v[240:241], v169 offset:54272
	ds_read_b64_tr_b16 v[242:243], v162 offset:56320
	s_waitcnt lgkmcnt(4)
	v_mfma_f32_32x32x16_bf16 v[48:63], v[232:235], v[132:135], v[48:63]
	ds_read_b64_tr_b16 v[232:233], v169 offset:54784
	ds_read_b64_tr_b16 v[234:235], v162 offset:56832
	s_waitcnt lgkmcnt(4)
	v_mfma_f32_32x32x16_bf16 v[32:47], v[236:239], v[132:135], v[32:47]
	ds_read_b64_tr_b16 v[236:237], v169 offset:40960
	ds_read_b64_tr_b16 v[238:239], v162 offset:43008
	s_waitcnt lgkmcnt(4)
	v_mfma_f32_32x32x16_bf16 v[16:31], v[240:243], v[132:135], v[16:31]
	ds_read_b64_tr_b16 v[240:241], v169 offset:41472
	ds_read_b64_tr_b16 v[242:243], v162 offset:43520
	s_waitcnt lgkmcnt(4)
	v_mfma_f32_32x32x16_bf16 v[0:15], v[232:235], v[132:135], v[0:15]
	ds_read_b64_tr_b16 v[232:233], v169 offset:41984
	ds_read_b64_tr_b16 v[234:235], v162 offset:44032
	v_cvt_pk_bf16_f32 v132, v203, v204
	v_cvt_pk_bf16_f32 v133, v205, v206
	v_cvt_pk_bf16_f32 v134, v207, v209
	v_cvt_pk_bf16_f32 v135, v211, v219
	s_waitcnt lgkmcnt(4)
	v_mfma_f32_32x32x16_bf16 v[112:127], v[236:239], v[136:139], v[112:127]
	ds_read_b64_tr_b16 v[236:237], v169 offset:42496
	ds_read_b64_tr_b16 v[238:239], v162 offset:44544
	s_waitcnt lgkmcnt(4)
	v_mfma_f32_32x32x16_bf16 v[96:111], v[240:243], v[136:139], v[96:111]
	ds_read_b64_tr_b16 v[240:241], v169 offset:57344
	ds_read_b64_tr_b16 v[242:243], v162 offset:59392
	s_waitcnt lgkmcnt(4)
	v_mfma_f32_32x32x16_bf16 v[80:95], v[232:235], v[136:139], v[80:95]
	ds_read_b64_tr_b16 v[232:233], v169 offset:57856
	ds_read_b64_tr_b16 v[234:235], v162 offset:59904
	s_waitcnt lgkmcnt(4)
	v_mfma_f32_32x32x16_bf16 v[64:79], v[236:239], v[136:139], v[64:79]
	ds_read_b64_tr_b16 v[236:237], v169 offset:58368
	ds_read_b64_tr_b16 v[238:239], v162 offset:60416
	s_waitcnt lgkmcnt(4)
	v_mfma_f32_32x32x16_bf16 v[48:63], v[240:243], v[136:139], v[48:63]
	ds_read_b64_tr_b16 v[240:241], v169 offset:58880
	ds_read_b64_tr_b16 v[242:243], v162 offset:60928
	s_waitcnt lgkmcnt(4)
	v_mfma_f32_32x32x16_bf16 v[32:47], v[232:235], v[136:139], v[32:47]
	ds_read_b64_tr_b16 v[232:233], v169 offset:45056
	ds_read_b64_tr_b16 v[234:235], v162 offset:47104
	s_waitcnt lgkmcnt(4)
	v_mfma_f32_32x32x16_bf16 v[16:31], v[236:239], v[136:139], v[16:31]
	ds_read_b64_tr_b16 v[236:237], v169 offset:45568
	ds_read_b64_tr_b16 v[238:239], v162 offset:47616
	s_waitcnt lgkmcnt(4)
	v_mfma_f32_32x32x16_bf16 v[0:15], v[240:243], v[136:139], v[0:15]
	ds_read_b64_tr_b16 v[240:241], v169 offset:46080
	ds_read_b64_tr_b16 v[242:243], v162 offset:48128
	v_cvt_pk_bf16_f32 v136, v187, v188
	v_cvt_pk_bf16_f32 v137, v189, v190
	v_cvt_pk_bf16_f32 v138, v192, v196
	v_cvt_pk_bf16_f32 v139, v200, v202
	s_waitcnt lgkmcnt(4)
	v_mfma_f32_32x32x16_bf16 v[112:127], v[232:235], v[156:159], v[112:127]
	ds_read_b64_tr_b16 v[232:233], v169 offset:46592
	ds_read_b64_tr_b16 v[234:235], v162 offset:48640
	s_waitcnt lgkmcnt(4)
; #define MFMA32(a, b, c) __builtin_amdgcn_mfma_f32_32x32x16_bf16((a), (b), (c), 0, 0, 0)
; DI void xattn_unit(const bf16_t* __restrict__ Qg, const bf16_t* __restrict__ Kg, const bf16_t* __restrict__ Vg, bf16_t* __restrict__ Og, lds_t* shm) {
;     ...
; #pragma unroll
;   for (int t = 0; t < 4; ++t) {
;     if (t == 1) { __builtin_amdgcn_sched_barrier(0); asm volatile("s_waitcnt vmcnt(0)" ::: "memory"); __syncthreads(); __builtin_amdgcn_sched_barrier(0); }
;     const unsigned vbase = (t == 0) ? 131072u : (unsigned)t * 32768u;
; #pragma unroll
;     for (int ks = 0; ks < 4; ++ks)
; #pragma unroll
;       for (int c = 0; c < NC; ++c) {
;         const unsigned vo = vbase + (c >> 2) * 16384 + 512 * (c & 3) + 4096 * ks;
;         const bf16x8 vf = tr_pair(shm + vo + va0, shm + vo + 2048 + va1);
;         O[c] = MFMA32(vf, P[t][ks >> 1][ks & 1], O[c]);
;       }
	v_mfma_f32_32x32x16_bf16 v[96:111], v[236:239], v[156:159], v[96:111]
	ds_read_b64_tr_b16 v[236:237], v169 offset:61440
	ds_read_b64_tr_b16 v[238:239], v162 offset:63488
	s_waitcnt lgkmcnt(4)
	v_mfma_f32_32x32x16_bf16 v[80:95], v[240:243], v[156:159], v[80:95]
	ds_read_b64_tr_b16 v[240:241], v169 offset:61952
	ds_read_b64_tr_b16 v[242:243], v162 offset:64000
	s_waitcnt lgkmcnt(4)
	v_mfma_f32_32x32x16_bf16 v[64:79], v[232:235], v[156:159], v[64:79]
	ds_read_b64_tr_b16 v[232:233], v169 offset:62464
	ds_read_b64_tr_b16 v[234:235], v162 offset:64512
	s_waitcnt lgkmcnt(4)
	v_mfma_f32_32x32x16_bf16 v[48:63], v[236:239], v[156:159], v[48:63]
	ds_read_b64_tr_b16 v[236:237], v169 offset:62976
	ds_read_b64_tr_b16 v[238:239], v162 offset:65024
	s_waitcnt lgkmcnt(4)
	v_mfma_f32_32x32x16_bf16 v[32:47], v[240:243], v[156:159], v[32:47]
	v_add_u32_e32 v240, s0, v170
	v_readlane_b32 s0, v255, 23
	s_nop 1
	v_add3_u32 v240, v240, v166, v160
	s_nop 0
	v_add_u32_e32 v241, s0, v170
	v_add3_u32 v242, v241, v165, v160
	ds_read_b64_tr_b16 v[240:241], v240
	ds_read_b64_tr_b16 v[242:243], v242
	s_add_i32 s0, 0, 0x10200
	s_waitcnt lgkmcnt(4)
	v_mfma_f32_32x32x16_bf16 v[16:31], v[232:235], v[156:159], v[16:31]
	v_add_u32_e32 v232, s0, v170
	v_readlane_b32 s0, v255, 24
	s_nop 1
	v_add3_u32 v232, v232, v166, v160
	s_nop 0
	v_add_u32_e32 v233, s0, v170
	v_add3_u32 v234, v233, v165, v160
	ds_read_b64_tr_b16 v[232:233], v232
	ds_read_b64_tr_b16 v[234:235], v234
	s_add_i32 s0, 0, 0x10400
	s_waitcnt lgkmcnt(4)
	v_mfma_f32_32x32x16_bf16 v[0:15], v[236:239], v[156:159], v[0:15]
	v_add_u32_e32 v236, s0, v170
	v_readlane_b32 s0, v255, 25
	s_nop 1
	v_add3_u32 v236, v236, v166, v160
	s_nop 0
	v_add_u32_e32 v237, s0, v170
	v_add3_u32 v238, v237, v165, v160
	ds_read_b64_tr_b16 v[236:237], v236
	ds_read_b64_tr_b16 v[238:239], v238
	s_add_i32 s0, 0, 0x10600
	s_waitcnt lgkmcnt(4)
	v_mfma_f32_32x32x16_bf16 v[112:127], v[240:243], v[152:155], v[112:127]
	v_add_u32_e32 v240, s0, v170
	v_readlane_b32 s0, v255, 26
	s_nop 1
	v_add3_u32 v240, v240, v166, v160
	s_nop 0
	v_add_u32_e32 v241, s0, v170
	v_add3_u32 v242, v241, v165, v160
	ds_read_b64_tr_b16 v[240:241], v240
	ds_read_b64_tr_b16 v[242:243], v242
	s_add_i32 s0, 0, 0x14000
	s_waitcnt lgkmcnt(4)
	v_mfma_f32_32x32x16_bf16 v[96:111], v[232:235], v[152:155], v[96:111]
	v_add_u32_e32 v232, s0, v170
	v_readlane_b32 s0, v255, 27
	s_nop 1
	v_add3_u32 v232, v232, v166, v160
	s_nop 0
	v_add_u32_e32 v233, s0, v170
	v_add3_u32 v234, v233, v165, v160
	ds_read_b64_tr_b16 v[232:233], v232
	ds_read_b64_tr_b16 v[234:235], v234
	s_add_i32 s0, 0, 0x14200
	s_waitcnt lgkmcnt(4)
	v_mfma_f32_32x32x16_bf16 v[80:95], v[236:239], v[152:155], v[80:95]
	v_add_u32_e32 v236, s0, v170
	v_readlane_b32 s0, v255, 28
	s_nop 1
	v_add3_u32 v236, v236, v166, v160
	s_nop 0
	v_add_u32_e32 v237, s0, v170
	v_add3_u32 v238, v237, v165, v160
	ds_read_b64_tr_b16 v[236:237], v236
	ds_read_b64_tr_b16 v[238:239], v238
	s_add_i32 s0, 0, 0x14400
	s_waitcnt lgkmcnt(4)
	v_mfma_f32_32x32x16_bf16 v[64:79], v[240:243], v[152:155], v[64:79]
	v_add_u32_e32 v240, s0, v170
	v_readlane_b32 s0, v255, 29
	s_nop 1
	v_add3_u32 v240, v240, v166, v160
	s_nop 0
	v_add_u32_e32 v241, s0, v170
	v_add3_u32 v242, v241, v165, v160
	ds_read_b64_tr_b16 v[240:241], v240
	ds_read_b64_tr_b16 v[242:243], v242
	s_add_i32 s0, 0, 0x14600
	s_waitcnt lgkmcnt(4)
	v_mfma_f32_32x32x16_bf16 v[48:63], v[232:235], v[152:155], v[48:63]
	v_add_u32_e32 v232, s0, v170
	v_readlane_b32 s0, v255, 30
	s_nop 1
	v_add3_u32 v232, v232, v166, v160
	s_nop 0
	v_add_u32_e32 v233, s0, v170
	v_add3_u32 v234, v233, v165, v160
	ds_read_b64_tr_b16 v[232:233], v232
	ds_read_b64_tr_b16 v[234:235], v234
	v_readlane_b32 s0, v255, 31
	s_nop 1
	s_waitcnt lgkmcnt(4)
	v_mfma_f32_32x32x16_bf16 v[32:47], v[236:239], v[152:155], v[32:47]
	v_add_u32_e32 v236, s0, v170
	v_readlane_b32 s0, v255, 32
	s_nop 1
	v_add3_u32 v236, v236, v166, v160
	s_nop 0
	v_add_u32_e32 v237, s0, v170
	v_add3_u32 v238, v237, v165, v160
	ds_read_b64_tr_b16 v[236:237], v236
	ds_read_b64_tr_b16 v[238:239], v238
	v_readlane_b32 s0, v255, 33
	s_nop 1
	s_waitcnt lgkmcnt(4)
	v_mfma_f32_32x32x16_bf16 v[16:31], v[240:243], v[152:155], v[16:31]
	v_add_u32_e32 v240, s0, v170
	v_readlane_b32 s0, v255, 34
	s_nop 1
	v_add3_u32 v240, v240, v166, v160
	s_nop 0
	v_add_u32_e32 v241, s0, v170
	v_add3_u32 v242, v241, v165, v160
	ds_read_b64_tr_b16 v[240:241], v240
	ds_read_b64_tr_b16 v[242:243], v242
	v_readlane_b32 s0, v255, 35
	s_nop 1
	s_waitcnt lgkmcnt(4)
	v_mfma_f32_32x32x16_bf16 v[0:15], v[232:235], v[152:155], v[0:15]
	v_add_u32_e32 v232, s0, v170
	v_readlane_b32 s0, v255, 36
	s_nop 1
	v_add3_u32 v232, v232, v166, v160
	s_nop 0
	v_add_u32_e32 v233, s0, v170
	v_add3_u32 v234, v233, v165, v160
	ds_read_b64_tr_b16 v[232:233], v232
	ds_read_b64_tr_b16 v[234:235], v234
	v_readlane_b32 s0, v255, 37
	s_nop 1
	s_waitcnt lgkmcnt(4)
	v_mfma_f32_32x32x16_bf16 v[112:127], v[236:239], v[148:151], v[112:127]
	v_add_u32_e32 v236, s0, v170
	v_readlane_b32 s0, v255, 38
	s_nop 1
	v_add3_u32 v236, v236, v166, v160
	s_nop 0
	v_add_u32_e32 v237, s0, v170
	v_add3_u32 v238, v237, v165, v160
	ds_read_b64_tr_b16 v[236:237], v236
	ds_read_b64_tr_b16 v[238:239], v238
	v_readlane_b32 s0, v255, 39
	s_nop 1
	s_waitcnt lgkmcnt(4)
	v_mfma_f32_32x32x16_bf16 v[96:111], v[240:243], v[148:151], v[96:111]
	v_add_u32_e32 v240, s0, v170
	v_readlane_b32 s0, v255, 40
	s_nop 1
	v_add3_u32 v240, v240, v166, v160
	s_nop 0
	v_add_u32_e32 v241, s0, v170
	v_add3_u32 v242, v241, v165, v160
	ds_read_b64_tr_b16 v[240:241], v240
	ds_read_b64_tr_b16 v[242:243], v242
	v_readlane_b32 s0, v255, 41
	s_nop 1
	s_waitcnt lgkmcnt(4)
; #define MFMA32(a, b, c) __builtin_amdgcn_mfma_f32_32x32x16_bf16((a), (b), (c), 0, 0, 0)
; DI void xattn_unit(const bf16_t* __restrict__ Qg, const bf16_t* __restrict__ Kg, const bf16_t* __restrict__ Vg, bf16_t* __restrict__ Og, lds_t* shm) {
;     ...
; #pragma unroll
;   for (int t = 0; t < 4; ++t) {
;     if (t == 1) { __builtin_amdgcn_sched_barrier(0); asm volatile("s_waitcnt vmcnt(0)" ::: "memory"); __syncthreads(); __builtin_amdgcn_sched_barrier(0); }
;     const unsigned vbase = (t == 0) ? 131072u : (unsigned)t * 32768u;
; #pragma unroll
;     for (int ks = 0; ks < 4; ++ks)
; #pragma unroll
;       for (int c = 0; c < NC; ++c) {
;         const unsigned vo = vbase + (c >> 2) * 16384 + 512 * (c & 3) + 4096 * ks;
;         const bf16x8 vf = tr_pair(shm + vo + va0, shm + vo + 2048 + va1);
;         O[c] = MFMA32(vf, P[t][ks >> 1][ks & 1], O[c]);
;       }
	v_mfma_f32_32x32x16_bf16 v[80:95], v[232:235], v[148:151], v[80:95]
	v_add_u32_e32 v232, s0, v170
	v_readlane_b32 s0, v255, 42
	s_nop 1
	v_add3_u32 v232, v232, v166, v160
	s_nop 0
	v_add_u32_e32 v233, s0, v170
	v_add3_u32 v234, v233, v165, v160
	ds_read_b64_tr_b16 v[232:233], v232
	ds_read_b64_tr_b16 v[234:235], v234
	v_readlane_b32 s0, v255, 43
	s_nop 1
	s_waitcnt lgkmcnt(4)
	v_mfma_f32_32x32x16_bf16 v[64:79], v[236:239], v[148:151], v[64:79]
	v_add_u32_e32 v236, s0, v170
	v_readlane_b32 s0, v255, 44
	s_nop 1
	v_add3_u32 v236, v236, v166, v160
	s_nop 0
	v_add_u32_e32 v237, s0, v170
	v_add3_u32 v238, v237, v165, v160
	ds_read_b64_tr_b16 v[236:237], v236
	ds_read_b64_tr_b16 v[238:239], v238
	v_readlane_b32 s0, v255, 45
	s_nop 1
	s_waitcnt lgkmcnt(4)
	v_mfma_f32_32x32x16_bf16 v[48:63], v[240:243], v[148:151], v[48:63]
	v_add_u32_e32 v240, s0, v170
	v_readlane_b32 s0, v255, 46
	s_nop 1
	v_add3_u32 v240, v240, v166, v160
	s_nop 0
	v_add_u32_e32 v241, s0, v170
	v_add3_u32 v242, v241, v165, v160
	ds_read_b64_tr_b16 v[240:241], v240
	ds_read_b64_tr_b16 v[242:243], v242
	s_add_i32 s0, 0, 0x12000
	s_waitcnt lgkmcnt(4)
	v_mfma_f32_32x32x16_bf16 v[32:47], v[232:235], v[148:151], v[32:47]
	v_add_u32_e32 v232, s0, v170
	v_readlane_b32 s0, v255, 47
	s_nop 1
	v_add3_u32 v232, v232, v166, v160
	s_nop 0
	v_add_u32_e32 v233, s0, v170
	v_add3_u32 v234, v233, v165, v160
	ds_read_b64_tr_b16 v[232:233], v232
	ds_read_b64_tr_b16 v[234:235], v234
	s_add_i32 s0, 0, 0x12200
	s_waitcnt lgkmcnt(4)
	v_mfma_f32_32x32x16_bf16 v[16:31], v[236:239], v[148:151], v[16:31]
	v_add_u32_e32 v236, s0, v170
	v_readlane_b32 s0, v255, 48
	s_nop 1
	v_add3_u32 v236, v236, v166, v160
	s_nop 0
	v_add_u32_e32 v237, s0, v170
	v_add3_u32 v238, v237, v165, v160
	ds_read_b64_tr_b16 v[236:237], v236
	ds_read_b64_tr_b16 v[238:239], v238
	s_add_i32 s0, 0, 0x12400
	s_waitcnt lgkmcnt(4)
	v_mfma_f32_32x32x16_bf16 v[0:15], v[240:243], v[148:151], v[0:15]
	v_add_u32_e32 v240, s0, v170
	v_readlane_b32 s0, v255, 49
	s_nop 1
	v_add3_u32 v240, v240, v166, v160
	s_nop 0
	v_add_u32_e32 v241, s0, v170
	v_add3_u32 v242, v241, v165, v160
	ds_read_b64_tr_b16 v[240:241], v240
	ds_read_b64_tr_b16 v[242:243], v242
	s_add_i32 s0, 0, 0x12600
	s_waitcnt lgkmcnt(4)
	v_mfma_f32_32x32x16_bf16 v[112:127], v[232:235], v[140:143], v[112:127]
	v_add_u32_e32 v232, s0, v170
	v_readlane_b32 s0, v255, 50
	s_nop 1
	v_add3_u32 v232, v232, v166, v160
	s_nop 0
	v_add_u32_e32 v233, s0, v170
	v_add3_u32 v234, v233, v165, v160
	ds_read_b64_tr_b16 v[232:233], v232
	ds_read_b64_tr_b16 v[234:235], v234
	s_add_i32 s0, 0, 0x16000
	s_waitcnt lgkmcnt(4)
	v_mfma_f32_32x32x16_bf16 v[96:111], v[236:239], v[140:143], v[96:111]
	v_add_u32_e32 v236, s0, v170
	v_readlane_b32 s0, v255, 51
	s_nop 1
	v_add3_u32 v236, v236, v166, v160
	s_nop 0
	v_add_u32_e32 v237, s0, v170
	v_add3_u32 v238, v237, v165, v160
	ds_read_b64_tr_b16 v[236:237], v236
	ds_read_b64_tr_b16 v[238:239], v238
	s_add_i32 s0, 0, 0x16200
	s_waitcnt lgkmcnt(4)
	v_mfma_f32_32x32x16_bf16 v[80:95], v[240:243], v[140:143], v[80:95]
	v_add_u32_e32 v240, s0, v170
	v_readlane_b32 s0, v255, 52
	s_nop 1
	v_add3_u32 v240, v240, v166, v160
	s_nop 0
	v_add_u32_e32 v241, s0, v170
	v_add3_u32 v242, v241, v165, v160
	ds_read_b64_tr_b16 v[240:241], v240
	ds_read_b64_tr_b16 v[242:243], v242
	s_add_i32 s0, 0, 0x16400
	s_waitcnt lgkmcnt(4)
	v_mfma_f32_32x32x16_bf16 v[64:79], v[232:235], v[140:143], v[64:79]
	v_add_u32_e32 v232, s0, v170
	v_readlane_b32 s0, v255, 53
	s_nop 1
	v_add3_u32 v232, v232, v166, v160
	s_nop 0
	v_add_u32_e32 v233, s0, v170
	v_add3_u32 v234, v233, v165, v160
	ds_read_b64_tr_b16 v[232:233], v232
	ds_read_b64_tr_b16 v[234:235], v234
	s_add_i32 s0, 0, 0x16600
	s_waitcnt lgkmcnt(4)
	v_mfma_f32_32x32x16_bf16 v[48:63], v[236:239], v[140:143], v[48:63]
	v_add_u32_e32 v236, s0, v170
	v_readlane_b32 s0, v255, 54
	s_nop 1
	v_add3_u32 v236, v236, v166, v160
	s_nop 0
	v_add_u32_e32 v237, s0, v170
	v_add3_u32 v238, v237, v165, v160
	ds_read_b64_tr_b16 v[236:237], v236
	ds_read_b64_tr_b16 v[238:239], v238
	v_readlane_b32 s0, v255, 55
	s_nop 1
	s_waitcnt lgkmcnt(4)
	v_mfma_f32_32x32x16_bf16 v[32:47], v[240:243], v[140:143], v[32:47]
	v_add_u32_e32 v240, s0, v170
	v_readlane_b32 s0, v255, 56
	s_nop 1
	v_add3_u32 v240, v240, v166, v160
	v_add_u32_e32 v241, s0, v170
	v_add3_u32 v242, v241, v165, v160
	ds_read_b64_tr_b16 v[240:241], v240
	ds_read_b64_tr_b16 v[242:243], v242
	v_readlane_b32 s0, v255, 57
	s_nop 1
	s_waitcnt lgkmcnt(4)
	v_mfma_f32_32x32x16_bf16 v[16:31], v[232:235], v[140:143], v[16:31]
	v_add_u32_e32 v232, s0, v170
	v_readlane_b32 s0, v255, 58
	s_nop 1
	v_add3_u32 v232, v232, v166, v160
	v_add_u32_e32 v233, s0, v170
	v_add3_u32 v234, v233, v165, v160
	ds_read_b64_tr_b16 v[232:233], v232
	ds_read_b64_tr_b16 v[234:235], v234
	v_readlane_b32 s0, v255, 59
	s_nop 1
	s_waitcnt lgkmcnt(4)
	v_mfma_f32_32x32x16_bf16 v[0:15], v[236:239], v[140:143], v[0:15]
	v_add_u32_e32 v236, s0, v170
	v_readlane_b32 s0, v255, 60
	s_nop 1
	v_add3_u32 v236, v236, v166, v160
	v_add_u32_e32 v237, s0, v170
	v_add3_u32 v238, v237, v165, v160
	ds_read_b64_tr_b16 v[236:237], v236
	ds_read_b64_tr_b16 v[238:239], v238
	v_readlane_b32 s0, v255, 61
	s_nop 1
	v_cvt_pk_bf16_f32 v140, v171, v172
	s_waitcnt lgkmcnt(4)
	v_mfma_f32_32x32x16_bf16 v[112:127], v[240:243], v[144:147], v[112:127]
	v_add_u32_e32 v240, s0, v170
	v_readlane_b32 s0, v255, 62
	s_nop 1
	v_add3_u32 v240, v240, v166, v160
	v_add_u32_e32 v241, s0, v170
	v_add3_u32 v242, v241, v165, v160
	ds_read_b64_tr_b16 v[240:241], v240
	ds_read_b64_tr_b16 v[242:243], v242
	v_cvt_pk_bf16_f32 v141, v173, v175
	s_waitcnt lgkmcnt(4)
; #define MFMA32(a, b, c) __builtin_amdgcn_mfma_f32_32x32x16_bf16((a), (b), (c), 0, 0, 0)
; DI void xattn_unit(const bf16_t* __restrict__ Qg, const bf16_t* __restrict__ Kg, const bf16_t* __restrict__ Vg, bf16_t* __restrict__ Og, lds_t* shm) {
;     ...
; #pragma unroll
;   for (int t = 0; t < 4; ++t) {
;     if (t == 1) { __builtin_amdgcn_sched_barrier(0); asm volatile("s_waitcnt vmcnt(0)" ::: "memory"); __syncthreads(); __builtin_amdgcn_sched_barrier(0); }
;     const unsigned vbase = (t == 0) ? 131072u : (unsigned)t * 32768u;
; #pragma unroll
;     for (int ks = 0; ks < 4; ++ks)
; #pragma unroll
;       for (int c = 0; c < NC; ++c) {
;         const unsigned vo = vbase + (c >> 2) * 16384 + 512 * (c & 3) + 4096 * ks;
;         const bf16x8 vf = tr_pair(shm + vo + va0, shm + vo + 2048 + va1);
;         O[c] = MFMA32(vf, P[t][ks >> 1][ks & 1], O[c]);
;       }
	v_mfma_f32_32x32x16_bf16 v[96:111], v[232:235], v[144:147], v[96:111]
	v_add_u32_e32 v232, s83, v170
	v_add_u32_e32 v233, s84, v170
	v_add3_u32 v232, v232, v166, v160
	v_add3_u32 v234, v233, v165, v160
	ds_read_b64_tr_b16 v[232:233], v232
	ds_read_b64_tr_b16 v[234:235], v234
	s_add_i32 s0, 0, 0x18000
	v_cvt_pk_bf16_f32 v142, v182, v184
	s_waitcnt lgkmcnt(4)
	v_mfma_f32_32x32x16_bf16 v[80:95], v[236:239], v[144:147], v[80:95]
	v_add_u32_e32 v236, s85, v170
	v_add_u32_e32 v237, s86, v170
	v_add3_u32 v236, v236, v166, v160
	v_add3_u32 v238, v237, v165, v160
	ds_read_b64_tr_b16 v[236:237], v236
	ds_read_b64_tr_b16 v[238:239], v238
	v_cvt_pk_bf16_f32 v143, v185, v186
	s_waitcnt lgkmcnt(4)
	v_mfma_f32_32x32x16_bf16 v[64:79], v[240:243], v[144:147], v[64:79]
	v_add_u32_e32 v240, s87, v170
	v_add_u32_e32 v241, s88, v170
	v_add3_u32 v240, v240, v166, v160
	v_add3_u32 v242, v241, v165, v160
	ds_read_b64_tr_b16 v[240:241], v240
	ds_read_b64_tr_b16 v[242:243], v242
	s_waitcnt lgkmcnt(4)
	v_mfma_f32_32x32x16_bf16 v[48:63], v[232:235], v[144:147], v[48:63]
	v_add_u32_e32 v232, s89, v170
	v_add_u32_e32 v233, s90, v170
	v_add3_u32 v232, v232, v166, v160
	v_add3_u32 v234, v233, v165, v160
	ds_read_b64_tr_b16 v[232:233], v232
	ds_read_b64_tr_b16 v[234:235], v234
	s_waitcnt lgkmcnt(4)
	v_mfma_f32_32x32x16_bf16 v[32:47], v[236:239], v[144:147], v[32:47]
	v_add_u32_e32 v236, s0, v170
	v_add_u32_e32 v237, s91, v170
	v_add3_u32 v236, v236, v166, v160
	v_add3_u32 v238, v237, v165, v160
	ds_read_b64_tr_b16 v[236:237], v236
	ds_read_b64_tr_b16 v[238:239], v238
	s_add_i32 s0, 0, 0x18200
	s_waitcnt lgkmcnt(4)
	v_mfma_f32_32x32x16_bf16 v[16:31], v[240:243], v[144:147], v[16:31]
	v_add_u32_e32 v240, s0, v170
	v_add_u32_e32 v241, s92, v170
	v_add3_u32 v240, v240, v166, v160
	v_add3_u32 v242, v241, v165, v160
	ds_read_b64_tr_b16 v[240:241], v240
	ds_read_b64_tr_b16 v[242:243], v242
	s_add_i32 s0, 0, 0x18400
	s_waitcnt lgkmcnt(4)
	v_mfma_f32_32x32x16_bf16 v[0:15], v[232:235], v[144:147], v[0:15]
	v_add_u32_e32 v232, s0, v170
	v_add_u32_e32 v233, s93, v170
	v_add3_u32 v232, v232, v166, v160
	v_add3_u32 v234, v233, v165, v160
	ds_read_b64_tr_b16 v[232:233], v232
	ds_read_b64_tr_b16 v[234:235], v234
	s_add_i32 s0, 0, 0x18600
	v_cvt_pk_bf16_f32 v128, v222, v223
	s_waitcnt lgkmcnt(4)
	v_mfma_f32_32x32x16_bf16 v[112:127], v[236:239], v[140:143], v[112:127]
	v_add_u32_e32 v236, s0, v170
	v_add_u32_e32 v237, s94, v170
	v_add3_u32 v236, v236, v166, v160
	v_add3_u32 v238, v237, v165, v160
	ds_read_b64_tr_b16 v[236:237], v236
	ds_read_b64_tr_b16 v[238:239], v238
	s_add_i32 s0, 0, 0x1c000
	v_cvt_pk_bf16_f32 v129, v224, v225
	s_waitcnt lgkmcnt(4)
	v_mfma_f32_32x32x16_bf16 v[96:111], v[240:243], v[140:143], v[96:111]
	v_add_u32_e32 v240, s0, v170
	v_add_u32_e32 v241, s95, v170
	v_add3_u32 v240, v240, v166, v160
	v_add3_u32 v242, v241, v165, v160
	ds_read_b64_tr_b16 v[240:241], v240
	ds_read_b64_tr_b16 v[242:243], v242
	s_add_i32 s0, 0, 0x1c200
	v_cvt_pk_bf16_f32 v130, v226, v228
	s_waitcnt lgkmcnt(4)
	v_mfma_f32_32x32x16_bf16 v[80:95], v[232:235], v[140:143], v[80:95]
	v_add_u32_e32 v232, s0, v170
	v_add_u32_e32 v233, s96, v170
	v_add3_u32 v232, v232, v166, v160
	v_add3_u32 v234, v233, v165, v160
	ds_read_b64_tr_b16 v[232:233], v232
	ds_read_b64_tr_b16 v[234:235], v234
	s_add_i32 s0, 0, 0x1c400
	v_cvt_pk_bf16_f32 v131, v229, v230
	s_waitcnt lgkmcnt(4)
	v_mfma_f32_32x32x16_bf16 v[64:79], v[236:239], v[140:143], v[64:79]
	v_add_u32_e32 v236, s0, v170
	v_add_u32_e32 v237, s97, v170
	v_add3_u32 v236, v236, v166, v160
	v_add3_u32 v238, v237, v165, v160
	ds_read_b64_tr_b16 v[236:237], v236
	ds_read_b64_tr_b16 v[238:239], v238
	s_add_i32 s0, 0, 0x1c600
	s_waitcnt lgkmcnt(4)
	v_mfma_f32_32x32x16_bf16 v[48:63], v[240:243], v[140:143], v[48:63]
	v_add_u32_e32 v240, s0, v170
	v_add_u32_e32 v241, s8, v170
	v_add3_u32 v240, v240, v166, v160
	v_add3_u32 v242, v241, v165, v160
	ds_read_b64_tr_b16 v[240:241], v240
	ds_read_b64_tr_b16 v[242:243], v242
	s_add_i32 s0, 0, 0x1a000
	s_waitcnt lgkmcnt(4)
	v_mfma_f32_32x32x16_bf16 v[32:47], v[232:235], v[140:143], v[32:47]
	v_add_u32_e32 v232, s9, v170
	v_add_u32_e32 v233, s10, v170
	v_add3_u32 v232, v232, v166, v160
	v_add3_u32 v234, v233, v165, v160
	ds_read_b64_tr_b16 v[232:233], v232
	ds_read_b64_tr_b16 v[234:235], v234
	s_waitcnt lgkmcnt(4)
	v_mfma_f32_32x32x16_bf16 v[16:31], v[236:239], v[140:143], v[16:31]
	v_add_u32_e32 v236, s11, v170
	v_add_u32_e32 v237, s18, v170
	v_add3_u32 v236, v236, v166, v160
	v_add3_u32 v238, v237, v165, v160
	ds_read_b64_tr_b16 v[236:237], v236
	ds_read_b64_tr_b16 v[238:239], v238
	s_waitcnt lgkmcnt(4)
	v_mfma_f32_32x32x16_bf16 v[0:15], v[240:243], v[140:143], v[0:15]
	v_add_u32_e32 v240, s19, v170
	v_add_u32_e32 v241, s34, v170
	v_add3_u32 v240, v240, v166, v160
	v_add3_u32 v242, v241, v165, v160
	ds_read_b64_tr_b16 v[240:241], v240
	ds_read_b64_tr_b16 v[242:243], v242
	s_waitcnt lgkmcnt(4)
	v_mfma_f32_32x32x16_bf16 v[112:127], v[232:235], v[136:139], v[112:127]
	v_add_u32_e32 v232, s20, v170
	v_add_u32_e32 v233, s21, v170
	v_add3_u32 v232, v232, v166, v160
	v_add3_u32 v234, v233, v165, v160
	ds_read_b64_tr_b16 v[232:233], v232
	ds_read_b64_tr_b16 v[234:235], v234
	s_waitcnt lgkmcnt(4)
	v_mfma_f32_32x32x16_bf16 v[96:111], v[236:239], v[136:139], v[96:111]
	v_add_u32_e32 v236, s22, v170
	v_add_u32_e32 v237, s23, v170
	v_add3_u32 v236, v236, v166, v160
	v_add3_u32 v238, v237, v165, v160
	ds_read_b64_tr_b16 v[236:237], v236
	ds_read_b64_tr_b16 v[238:239], v238
	s_waitcnt lgkmcnt(4)
; #define MFMA32(a, b, c) __builtin_amdgcn_mfma_f32_32x32x16_bf16((a), (b), (c), 0, 0, 0)
; DI void xattn_unit(const bf16_t* __restrict__ Qg, const bf16_t* __restrict__ Kg, const bf16_t* __restrict__ Vg, bf16_t* __restrict__ Og, lds_t* shm) {
;     ...
; #pragma unroll
;   for (int t = 0; t < 4; ++t) {
;     if (t == 1) { __builtin_amdgcn_sched_barrier(0); asm volatile("s_waitcnt vmcnt(0)" ::: "memory"); __syncthreads(); __builtin_amdgcn_sched_barrier(0); }
;     const unsigned vbase = (t == 0) ? 131072u : (unsigned)t * 32768u;
; #pragma unroll
;     for (int ks = 0; ks < 4; ++ks)
; #pragma unroll
;       for (int c = 0; c < NC; ++c) {
;         const unsigned vo = vbase + (c >> 2) * 16384 + 512 * (c & 3) + 4096 * ks;
;         const bf16x8 vf = tr_pair(shm + vo + va0, shm + vo + 2048 + va1);
;         O[c] = MFMA32(vf, P[t][ks >> 1][ks & 1], O[c]);
;       }
	v_mfma_f32_32x32x16_bf16 v[80:95], v[240:243], v[136:139], v[80:95]
	v_add_u32_e32 v240, s3, v170
	v_add_u32_e32 v241, s15, v170
	v_add3_u32 v240, v240, v166, v160
	v_add3_u32 v242, v241, v165, v160
	ds_read_b64_tr_b16 v[240:241], v240
	ds_read_b64_tr_b16 v[242:243], v242
	s_waitcnt lgkmcnt(4)
	v_mfma_f32_32x32x16_bf16 v[64:79], v[232:235], v[136:139], v[64:79]
	v_add_u32_e32 v232, s35, v170
	v_add_u32_e32 v233, s40, v170
	v_add3_u32 v232, v232, v166, v160
	v_add3_u32 v234, v233, v165, v160
	ds_read_b64_tr_b16 v[232:233], v232
	ds_read_b64_tr_b16 v[234:235], v234
	s_waitcnt lgkmcnt(4)
	v_mfma_f32_32x32x16_bf16 v[48:63], v[236:239], v[136:139], v[48:63]
	v_add_u32_e32 v236, s41, v170
	v_add_u32_e32 v237, s42, v170
	v_add3_u32 v236, v236, v166, v160
	v_add3_u32 v238, v237, v165, v160
	ds_read_b64_tr_b16 v[236:237], v236
	ds_read_b64_tr_b16 v[238:239], v238
	s_waitcnt lgkmcnt(4)
	v_mfma_f32_32x32x16_bf16 v[32:47], v[240:243], v[136:139], v[32:47]
	v_add_u32_e32 v240, s0, v170
	v_add_u32_e32 v241, s43, v170
	v_add3_u32 v240, v240, v166, v160
	v_add3_u32 v242, v241, v165, v160
	ds_read_b64_tr_b16 v[240:241], v240
	ds_read_b64_tr_b16 v[242:243], v242
	s_add_i32 s0, 0, 0x1a200
	s_waitcnt lgkmcnt(4)
	v_mfma_f32_32x32x16_bf16 v[16:31], v[232:235], v[136:139], v[16:31]
	v_add_u32_e32 v232, s0, v170
	v_add_u32_e32 v233, s46, v170
	v_add3_u32 v232, v232, v166, v160
	v_add3_u32 v234, v233, v165, v160
	ds_read_b64_tr_b16 v[232:233], v232
	ds_read_b64_tr_b16 v[234:235], v234
	s_add_i32 s0, 0, 0x1a400
	s_waitcnt lgkmcnt(4)
	v_mfma_f32_32x32x16_bf16 v[0:15], v[236:239], v[136:139], v[0:15]
	v_add_u32_e32 v236, s0, v170
	v_add_u32_e32 v237, s47, v170
	v_add3_u32 v236, v236, v166, v160
	v_add3_u32 v238, v237, v165, v160
	ds_read_b64_tr_b16 v[236:237], v236
	ds_read_b64_tr_b16 v[238:239], v238
	s_add_i32 s0, 0, 0x1a600
	s_waitcnt lgkmcnt(4)
	v_mfma_f32_32x32x16_bf16 v[112:127], v[240:243], v[132:135], v[112:127]
	v_add_u32_e32 v240, s0, v170
	v_add_u32_e32 v241, s48, v170
	v_add3_u32 v240, v240, v166, v160
	v_add3_u32 v242, v241, v165, v160
	ds_read_b64_tr_b16 v[240:241], v240
	ds_read_b64_tr_b16 v[242:243], v242
	s_add_i32 s0, 0, 0x1e000
	s_waitcnt lgkmcnt(4)
	v_mfma_f32_32x32x16_bf16 v[96:111], v[232:235], v[132:135], v[96:111]
	v_add_u32_e32 v232, s0, v170
	v_add_u32_e32 v233, s49, v170
	v_add3_u32 v232, v232, v166, v160
	v_add3_u32 v234, v233, v165, v160
	ds_read_b64_tr_b16 v[232:233], v232
	ds_read_b64_tr_b16 v[234:235], v234
	s_add_i32 s0, 0, 0x1e200
	s_waitcnt lgkmcnt(4)
	v_mfma_f32_32x32x16_bf16 v[80:95], v[236:239], v[132:135], v[80:95]
	v_add_u32_e32 v236, s0, v170
	v_add_u32_e32 v237, s52, v170
	v_add3_u32 v236, v236, v166, v160
	v_add3_u32 v238, v237, v165, v160
	ds_read_b64_tr_b16 v[236:237], v236
	ds_read_b64_tr_b16 v[238:239], v238
	s_add_i32 s0, 0, 0x1e400
	s_waitcnt lgkmcnt(4)
	v_mfma_f32_32x32x16_bf16 v[64:79], v[240:243], v[132:135], v[64:79]
	v_add_u32_e32 v240, s0, v170
	v_add_u32_e32 v241, s53, v170
	v_add3_u32 v240, v240, v166, v160
	v_add3_u32 v242, v241, v165, v160
	ds_read_b64_tr_b16 v[240:241], v240
	ds_read_b64_tr_b16 v[242:243], v242
	s_add_i32 s0, 0, 0x1e600
	s_waitcnt lgkmcnt(4)
	v_mfma_f32_32x32x16_bf16 v[48:63], v[232:235], v[132:135], v[48:63]
	v_add_u32_e32 v232, s0, v170
	v_add_u32_e32 v233, s54, v170
	v_add3_u32 v232, v232, v166, v160
	v_add3_u32 v234, v233, v165, v160
	ds_read_b64_tr_b16 v[232:233], v232
	ds_read_b64_tr_b16 v[234:235], v234
	s_waitcnt lgkmcnt(4)
	v_mfma_f32_32x32x16_bf16 v[32:47], v[236:239], v[132:135], v[32:47]
	v_add_u32_e32 v236, s55, v170
	v_add_u32_e32 v237, s56, v170
	v_add3_u32 v236, v236, v166, v160
	v_add3_u32 v238, v237, v165, v160
	ds_read_b64_tr_b16 v[236:237], v236
	ds_read_b64_tr_b16 v[238:239], v238
	s_waitcnt lgkmcnt(4)
	v_mfma_f32_32x32x16_bf16 v[16:31], v[240:243], v[132:135], v[16:31]
	v_add_u32_e32 v240, s57, v170
	v_add_u32_e32 v241, s58, v170
	v_add3_u32 v240, v240, v166, v160
	v_add3_u32 v242, v241, v165, v160
	ds_read_b64_tr_b16 v[240:241], v240
	ds_read_b64_tr_b16 v[242:243], v242
	s_waitcnt lgkmcnt(4)
	v_mfma_f32_32x32x16_bf16 v[0:15], v[232:235], v[132:135], v[0:15]
	v_add_u32_e32 v232, s59, v170
	v_add_u32_e32 v233, s60, v170
	v_add3_u32 v232, v232, v166, v160
	v_add3_u32 v234, v233, v165, v160
	ds_read_b64_tr_b16 v[232:233], v232
	ds_read_b64_tr_b16 v[234:235], v234
	s_waitcnt lgkmcnt(4)
	v_mfma_f32_32x32x16_bf16 v[112:127], v[236:239], v[128:131], v[112:127]
	v_add_u32_e32 v236, s61, v170
	v_add_u32_e32 v237, s62, v170
	v_add3_u32 v236, v236, v166, v160
	v_add3_u32 v238, v237, v165, v160
	ds_read_b64_tr_b16 v[236:237], v236
	ds_read_b64_tr_b16 v[238:239], v238
	s_waitcnt lgkmcnt(4)
	v_mfma_f32_32x32x16_bf16 v[96:111], v[240:243], v[128:131], v[96:111]
	v_add_u32_e32 v240, s63, v170
	v_add_u32_e32 v241, s64, v170
	v_add3_u32 v240, v240, v166, v160
	v_add3_u32 v242, v241, v165, v160
	ds_read_b64_tr_b16 v[240:241], v240
	ds_read_b64_tr_b16 v[242:243], v242
	s_waitcnt lgkmcnt(4)
	v_mfma_f32_32x32x16_bf16 v[80:95], v[232:235], v[128:131], v[80:95]
	v_add_u32_e32 v232, s65, v170
	v_add_u32_e32 v233, s6, v170
	v_add3_u32 v232, v232, v166, v160
	v_add3_u32 v234, v233, v165, v160
	ds_read_b64_tr_b16 v[232:233], v232
	ds_read_b64_tr_b16 v[234:235], v234
	s_waitcnt lgkmcnt(4)
	v_mfma_f32_32x32x16_bf16 v[64:79], v[236:239], v[128:131], v[64:79]
	v_add_u32_e32 v236, s7, v170
	v_add_u32_e32 v237, s66, v170
	v_add3_u32 v236, v236, v166, v160
	v_add3_u32 v238, v237, v165, v160
	ds_read_b64_tr_b16 v[236:237], v236
	ds_read_b64_tr_b16 v[238:239], v238
	s_waitcnt lgkmcnt(4)
; DI unsigned pk2(float lo, float hi) { bf2_t v = __builtin_convertvector((f32x2){lo, hi}, bf2_t); return __builtin_bit_cast(unsigned, v); }
; #define MFMA32(a, b, c) __builtin_amdgcn_mfma_f32_32x32x16_bf16((a), (b), (c), 0, 0, 0)
; DI void xattn_unit(const bf16_t* __restrict__ Qg, const bf16_t* __restrict__ Kg, const bf16_t* __restrict__ Vg, bf16_t* __restrict__ Og, lds_t* shm) {
;     ...
;     for (int ks = 0; ks < 4; ++ks)
; #pragma unroll
;       for (int c = 0; c < NC; ++c) {
;         const unsigned vo = vbase + (c >> 2) * 16384 + 512 * (c & 3) + 4096 * ks;
;         const bf16x8 vf = tr_pair(shm + vo + va0, shm + vo + 2048 + va1);
;         O[c] = MFMA32(vf, P[t][ks >> 1][ks & 1], O[c]);
;       }
;   }
;   const float inv = 1.0f / l;
;   const unsigned ooff = ((unsigned)l31 * (unsigned)LDQ + 4u * h) * 2u;
; #pragma unroll
;   for (int c = 0; c < NC; ++c)
; #pragma unroll
;     for (int g4 = 0; g4 < 4; ++g4) {
;       u32x2 w; w.x = pk2(O[c][4 * g4 + 0] * inv, O[c][4 * g4 + 1] * inv); w.y = pk2(O[c][4 * g4 + 2] * inv, O[c][4 * g4 + 3] * inv);
;       gst<u32x2>(Og + 32 * c + 8 * g4, ooff, w);
	v_mfma_f32_32x32x16_bf16 v[48:63], v[240:243], v[128:131], v[48:63]
	v_add_u32_e32 v240, s16, v170
	v_add_u32_e32 v241, s17, v170
	v_add3_u32 v240, v240, v166, v160
	v_add3_u32 v242, v241, v165, v160
	ds_read_b64_tr_b16 v[240:241], v240
	ds_read_b64_tr_b16 v[242:243], v242
	s_waitcnt lgkmcnt(4)
	v_mfma_f32_32x32x16_bf16 v[32:47], v[232:235], v[128:131], v[32:47]
	s_waitcnt lgkmcnt(2)
	v_mfma_f32_32x32x16_bf16 v[16:31], v[236:239], v[128:131], v[16:31]
	s_waitcnt lgkmcnt(0)
	v_mfma_f32_32x32x16_bf16 v[0:15], v[240:243], v[128:131], v[0:15]
	v_add_f32_e32 v128, v167, v168
	v_div_scale_f32 v129, s[0:1], v128, v128, 1.0
	v_rcp_f32_e32 v130, v129
	v_readlane_b32 s0, v254, 6
	s_mov_b32 s28, s0
	s_mul_i32 s0, s2, s0
	v_fma_f32 v131, -v129, v130, 1.0
	v_fmac_f32_e32 v130, v131, v130
	v_div_scale_f32 v131, vcc, 1.0, v128, 1.0
	v_mul_f32_e32 v132, v131, v130
	v_fma_f32 v133, -v129, v132, v131
	v_fmac_f32_e32 v132, v133, v130
	v_fma_f32 v129, -v129, v132, v131
	v_div_fmas_f32 v129, v129, v130, v132
	v_div_fixup_f32 v128, v129, v128, 1.0
	v_lshl_or_b32 v129, v163, 3, v164
	v_mbcnt_lo_u32_b32 v130, -1, 0
	v_mbcnt_hi_u32_b32 v130, -1, v130
	v_and_b32_e32 v131, 15, v130
	v_lshlrev_b32_e32 v131, 11, v131
	v_bfe_u32 v129, v130, 4, 1
	v_lshlrev_b32_e32 v129, 5, v129
	v_lshrrev_b32_e32 v130, 5, v130
	v_lshlrev_b32_e32 v130, 4, v130
	v_add3_u32 v130, v131, v129, v130
	v_add_u32_e32 v131, 0x8000, v130
	v_pk_mul_f32 v[112:113], v[128:129], v[112:113] op_sel_hi:[0,1]
	v_pk_mul_f32 v[114:115], v[128:129], v[114:115] op_sel_hi:[0,1]
	v_pk_mul_f32 v[116:117], v[128:129], v[116:117] op_sel_hi:[0,1]
	v_pk_mul_f32 v[118:119], v[128:129], v[118:119] op_sel_hi:[0,1]
	v_pk_mul_f32 v[120:121], v[128:129], v[120:121] op_sel_hi:[0,1]
	v_pk_mul_f32 v[122:123], v[128:129], v[122:123] op_sel_hi:[0,1]
	v_pk_mul_f32 v[124:125], v[128:129], v[124:125] op_sel_hi:[0,1]
	v_pk_mul_f32 v[126:127], v[128:129], v[126:127] op_sel_hi:[0,1]
	v_pk_mul_f32 v[96:97], v[128:129], v[96:97] op_sel_hi:[0,1]
	v_pk_mul_f32 v[98:99], v[128:129], v[98:99] op_sel_hi:[0,1]
	v_pk_mul_f32 v[100:101], v[128:129], v[100:101] op_sel_hi:[0,1]
	v_pk_mul_f32 v[102:103], v[128:129], v[102:103] op_sel_hi:[0,1]
	v_pk_mul_f32 v[104:105], v[128:129], v[104:105] op_sel_hi:[0,1]
	v_pk_mul_f32 v[106:107], v[128:129], v[106:107] op_sel_hi:[0,1]
	v_pk_mul_f32 v[108:109], v[128:129], v[108:109] op_sel_hi:[0,1]
	v_pk_mul_f32 v[110:111], v[128:129], v[110:111] op_sel_hi:[0,1]
	v_pk_mul_f32 v[80:81], v[128:129], v[80:81] op_sel_hi:[0,1]
	v_pk_mul_f32 v[82:83], v[128:129], v[82:83] op_sel_hi:[0,1]
	v_pk_mul_f32 v[84:85], v[128:129], v[84:85] op_sel_hi:[0,1]
	v_pk_mul_f32 v[86:87], v[128:129], v[86:87] op_sel_hi:[0,1]
	v_pk_mul_f32 v[88:89], v[128:129], v[88:89] op_sel_hi:[0,1]
	v_pk_mul_f32 v[90:91], v[128:129], v[90:91] op_sel_hi:[0,1]
	v_pk_mul_f32 v[92:93], v[128:129], v[92:93] op_sel_hi:[0,1]
	v_pk_mul_f32 v[94:95], v[128:129], v[94:95] op_sel_hi:[0,1]
	v_pk_mul_f32 v[64:65], v[128:129], v[64:65] op_sel_hi:[0,1]
	v_pk_mul_f32 v[66:67], v[128:129], v[66:67] op_sel_hi:[0,1]
	v_pk_mul_f32 v[68:69], v[128:129], v[68:69] op_sel_hi:[0,1]
	v_pk_mul_f32 v[70:71], v[128:129], v[70:71] op_sel_hi:[0,1]
	v_pk_mul_f32 v[72:73], v[128:129], v[72:73] op_sel_hi:[0,1]
	v_pk_mul_f32 v[74:75], v[128:129], v[74:75] op_sel_hi:[0,1]
	v_pk_mul_f32 v[76:77], v[128:129], v[76:77] op_sel_hi:[0,1]
	v_pk_mul_f32 v[78:79], v[128:129], v[78:79] op_sel_hi:[0,1]
	v_pk_mul_f32 v[48:49], v[128:129], v[48:49] op_sel_hi:[0,1]
	v_pk_mul_f32 v[50:51], v[128:129], v[50:51] op_sel_hi:[0,1]
	v_pk_mul_f32 v[52:53], v[128:129], v[52:53] op_sel_hi:[0,1]
	v_pk_mul_f32 v[54:55], v[128:129], v[54:55] op_sel_hi:[0,1]
	v_pk_mul_f32 v[56:57], v[128:129], v[56:57] op_sel_hi:[0,1]
	v_pk_mul_f32 v[58:59], v[128:129], v[58:59] op_sel_hi:[0,1]
	v_pk_mul_f32 v[60:61], v[128:129], v[60:61] op_sel_hi:[0,1]
	v_pk_mul_f32 v[62:63], v[128:129], v[62:63] op_sel_hi:[0,1]
	v_pk_mul_f32 v[32:33], v[128:129], v[32:33] op_sel_hi:[0,1]
	v_pk_mul_f32 v[34:35], v[128:129], v[34:35] op_sel_hi:[0,1]
	v_pk_mul_f32 v[36:37], v[128:129], v[36:37] op_sel_hi:[0,1]
	v_pk_mul_f32 v[38:39], v[128:129], v[38:39] op_sel_hi:[0,1]
	v_pk_mul_f32 v[40:41], v[128:129], v[40:41] op_sel_hi:[0,1]
	v_pk_mul_f32 v[42:43], v[128:129], v[42:43] op_sel_hi:[0,1]
	v_pk_mul_f32 v[44:45], v[128:129], v[44:45] op_sel_hi:[0,1]
	v_pk_mul_f32 v[46:47], v[128:129], v[46:47] op_sel_hi:[0,1]
	v_pk_mul_f32 v[16:17], v[128:129], v[16:17] op_sel_hi:[0,1]
	v_pk_mul_f32 v[18:19], v[128:129], v[18:19] op_sel_hi:[0,1]
	v_pk_mul_f32 v[20:21], v[128:129], v[20:21] op_sel_hi:[0,1]
	v_pk_mul_f32 v[22:23], v[128:129], v[22:23] op_sel_hi:[0,1]
	v_pk_mul_f32 v[24:25], v[128:129], v[24:25] op_sel_hi:[0,1]
	v_pk_mul_f32 v[26:27], v[128:129], v[26:27] op_sel_hi:[0,1]
	v_pk_mul_f32 v[28:29], v[128:129], v[28:29] op_sel_hi:[0,1]
	v_pk_mul_f32 v[30:31], v[128:129], v[30:31] op_sel_hi:[0,1]
	v_pk_mul_f32 v[0:1], v[128:129], v[0:1] op_sel_hi:[0,1]
	v_pk_mul_f32 v[2:3], v[128:129], v[2:3] op_sel_hi:[0,1]
	v_pk_mul_f32 v[4:5], v[128:129], v[4:5] op_sel_hi:[0,1]
	v_pk_mul_f32 v[6:7], v[128:129], v[6:7] op_sel_hi:[0,1]
	v_pk_mul_f32 v[8:9], v[128:129], v[8:9] op_sel_hi:[0,1]
	v_pk_mul_f32 v[10:11], v[128:129], v[10:11] op_sel_hi:[0,1]
	v_pk_mul_f32 v[12:13], v[128:129], v[12:13] op_sel_hi:[0,1]
	v_pk_mul_f32 v[14:15], v[128:129], v[14:15] op_sel_hi:[0,1]
	v_cvt_pk_bf16_f32 v112, v112, v113
	v_cvt_pk_bf16_f32 v113, v114, v115
	v_cvt_pk_bf16_f32 v114, v116, v117
	v_cvt_pk_bf16_f32 v115, v118, v119
	v_cvt_pk_bf16_f32 v120, v120, v121
	v_cvt_pk_bf16_f32 v121, v122, v123
; DI unsigned pk2(float lo, float hi) { bf2_t v = __builtin_convertvector((f32x2){lo, hi}, bf2_t); return __builtin_bit_cast(unsigned, v); }
; DI void xattn_unit(const bf16_t* __restrict__ Qg, const bf16_t* __restrict__ Kg, const bf16_t* __restrict__ Vg, bf16_t* __restrict__ Og, lds_t* shm) {
;     ...
;   const float inv = 1.0f / l;
;   const unsigned ooff = ((unsigned)l31 * (unsigned)LDQ + 4u * h) * 2u;
; #pragma unroll
;   for (int c = 0; c < NC; ++c)
; #pragma unroll
;     for (int g4 = 0; g4 < 4; ++g4) {
;       u32x2 w; w.x = pk2(O[c][4 * g4 + 0] * inv, O[c][4 * g4 + 1] * inv); w.y = pk2(O[c][4 * g4 + 2] * inv, O[c][4 * g4 + 3] * inv);
;       gst<u32x2>(Og + 32 * c + 8 * g4, ooff, w);
;     }
; DI void cross_attn_own_tiles(const Params& p, lds_t* shm) {
;     ...
;   for (int i = 0;; ++i) {
;     int pm, pn; if (!g8::tile_coords(i * (int)gridDim.x + (int)blockIdx.x, T_TOK / 256, 4, pm, pn)) break;
	v_cvt_pk_bf16_f32 v122, v124, v125
	v_cvt_pk_bf16_f32 v123, v126, v127
	s_nop 1
	v_permlane32_swap_b32_e32 v112, v114
	v_permlane32_swap_b32_e32 v113, v115
	v_permlane32_swap_b32_e32 v120, v122
	v_permlane32_swap_b32_e32 v121, v123
	s_nop 1
	v_permlane16_swap_b32_e32 v112, v120
	v_permlane16_swap_b32_e32 v113, v121
	v_permlane16_swap_b32_e32 v114, v122
	v_permlane16_swap_b32_e32 v115, v123
	global_store_dwordx4 v130, v[112:115], s[30:31] sc0 sc1
	global_store_dwordx4 v131, v[120:123], s[30:31] sc0 sc1
	v_cvt_pk_bf16_f32 v96, v96, v97
	v_cvt_pk_bf16_f32 v97, v98, v99
	v_cvt_pk_bf16_f32 v98, v100, v101
	v_cvt_pk_bf16_f32 v99, v102, v103
	v_cvt_pk_bf16_f32 v104, v104, v105
	v_cvt_pk_bf16_f32 v105, v106, v107
	v_cvt_pk_bf16_f32 v106, v108, v109
	v_cvt_pk_bf16_f32 v107, v110, v111
	s_nop 1
	v_permlane32_swap_b32_e32 v96, v98
	v_permlane32_swap_b32_e32 v97, v99
	v_permlane32_swap_b32_e32 v104, v106
	v_permlane32_swap_b32_e32 v105, v107
	s_nop 1
	v_permlane16_swap_b32_e32 v96, v104
	v_permlane16_swap_b32_e32 v97, v105
	v_permlane16_swap_b32_e32 v98, v106
	v_permlane16_swap_b32_e32 v99, v107
	global_store_dwordx4 v130, v[96:99], s[30:31] offset:64 sc0 sc1
	global_store_dwordx4 v131, v[104:107], s[30:31] offset:64 sc0 sc1
	v_cvt_pk_bf16_f32 v80, v80, v81
	v_cvt_pk_bf16_f32 v81, v82, v83
	v_cvt_pk_bf16_f32 v82, v84, v85
	v_cvt_pk_bf16_f32 v83, v86, v87
	v_cvt_pk_bf16_f32 v88, v88, v89
	v_cvt_pk_bf16_f32 v89, v90, v91
	v_cvt_pk_bf16_f32 v90, v92, v93
	v_cvt_pk_bf16_f32 v91, v94, v95
	s_nop 1
	v_permlane32_swap_b32_e32 v80, v82
	v_permlane32_swap_b32_e32 v81, v83
	v_permlane32_swap_b32_e32 v88, v90
	v_permlane32_swap_b32_e32 v89, v91
	s_nop 1
	v_permlane16_swap_b32_e32 v80, v88
	v_permlane16_swap_b32_e32 v81, v89
	v_permlane16_swap_b32_e32 v82, v90
	v_permlane16_swap_b32_e32 v83, v91
	global_store_dwordx4 v130, v[80:83], s[30:31] offset:128 sc0 sc1
	global_store_dwordx4 v131, v[88:91], s[30:31] offset:128 sc0 sc1
	v_cvt_pk_bf16_f32 v64, v64, v65
	v_cvt_pk_bf16_f32 v65, v66, v67
	v_cvt_pk_bf16_f32 v66, v68, v69
	v_cvt_pk_bf16_f32 v67, v70, v71
	v_cvt_pk_bf16_f32 v72, v72, v73
	v_cvt_pk_bf16_f32 v73, v74, v75
	v_cvt_pk_bf16_f32 v74, v76, v77
	v_cvt_pk_bf16_f32 v75, v78, v79
	s_nop 1
	v_permlane32_swap_b32_e32 v64, v66
	v_permlane32_swap_b32_e32 v65, v67
	v_permlane32_swap_b32_e32 v72, v74
	v_permlane32_swap_b32_e32 v73, v75
	s_nop 1
	v_permlane16_swap_b32_e32 v64, v72
	v_permlane16_swap_b32_e32 v65, v73
	v_permlane16_swap_b32_e32 v66, v74
	v_permlane16_swap_b32_e32 v67, v75
	global_store_dwordx4 v130, v[64:67], s[30:31] offset:192 sc0 sc1
	global_store_dwordx4 v131, v[72:75], s[30:31] offset:192 sc0 sc1
	v_cvt_pk_bf16_f32 v48, v48, v49
	v_cvt_pk_bf16_f32 v49, v50, v51
	v_cvt_pk_bf16_f32 v50, v52, v53
	v_cvt_pk_bf16_f32 v51, v54, v55
	v_cvt_pk_bf16_f32 v56, v56, v57
	v_cvt_pk_bf16_f32 v57, v58, v59
	v_cvt_pk_bf16_f32 v58, v60, v61
	v_cvt_pk_bf16_f32 v59, v62, v63
	s_nop 1
	v_permlane32_swap_b32_e32 v48, v50
	v_permlane32_swap_b32_e32 v49, v51
	v_permlane32_swap_b32_e32 v56, v58
	v_permlane32_swap_b32_e32 v57, v59
	s_nop 1
	v_permlane16_swap_b32_e32 v48, v56
	v_permlane16_swap_b32_e32 v49, v57
	v_permlane16_swap_b32_e32 v50, v58
	v_permlane16_swap_b32_e32 v51, v59
	global_store_dwordx4 v130, v[48:51], s[30:31] offset:256 sc0 sc1
	global_store_dwordx4 v131, v[56:59], s[30:31] offset:256 sc0 sc1
	v_cvt_pk_bf16_f32 v32, v32, v33
	v_cvt_pk_bf16_f32 v33, v34, v35
	v_cvt_pk_bf16_f32 v34, v36, v37
	v_cvt_pk_bf16_f32 v35, v38, v39
	v_cvt_pk_bf16_f32 v40, v40, v41
	v_cvt_pk_bf16_f32 v41, v42, v43
	v_cvt_pk_bf16_f32 v42, v44, v45
	v_cvt_pk_bf16_f32 v43, v46, v47
	s_nop 1
	v_permlane32_swap_b32_e32 v32, v34
	v_permlane32_swap_b32_e32 v33, v35
	v_permlane32_swap_b32_e32 v40, v42
	v_permlane32_swap_b32_e32 v41, v43
	s_nop 1
	v_permlane16_swap_b32_e32 v32, v40
	v_permlane16_swap_b32_e32 v33, v41
	v_permlane16_swap_b32_e32 v34, v42
	v_permlane16_swap_b32_e32 v35, v43
	global_store_dwordx4 v130, v[32:35], s[30:31] offset:320 sc0 sc1
	global_store_dwordx4 v131, v[40:43], s[30:31] offset:320 sc0 sc1
	v_cvt_pk_bf16_f32 v16, v16, v17
	v_cvt_pk_bf16_f32 v17, v18, v19
	v_cvt_pk_bf16_f32 v18, v20, v21
	v_cvt_pk_bf16_f32 v19, v22, v23
	v_cvt_pk_bf16_f32 v24, v24, v25
	v_cvt_pk_bf16_f32 v25, v26, v27
	v_cvt_pk_bf16_f32 v26, v28, v29
	v_cvt_pk_bf16_f32 v27, v30, v31
	s_nop 1
	v_permlane32_swap_b32_e32 v16, v18
	v_permlane32_swap_b32_e32 v17, v19
	v_permlane32_swap_b32_e32 v24, v26
	v_permlane32_swap_b32_e32 v25, v27
	s_nop 1
	v_permlane16_swap_b32_e32 v16, v24
	v_permlane16_swap_b32_e32 v17, v25
	v_permlane16_swap_b32_e32 v18, v26
	v_permlane16_swap_b32_e32 v19, v27
	global_store_dwordx4 v130, v[16:19], s[30:31] offset:384 sc0 sc1
	global_store_dwordx4 v131, v[24:27], s[30:31] offset:384 sc0 sc1
	v_cvt_pk_bf16_f32 v0, v0, v1
	v_cvt_pk_bf16_f32 v1, v2, v3
	v_cvt_pk_bf16_f32 v2, v4, v5
	v_cvt_pk_bf16_f32 v3, v6, v7
	v_cvt_pk_bf16_f32 v8, v8, v9
	v_cvt_pk_bf16_f32 v9, v10, v11
	v_cvt_pk_bf16_f32 v10, v12, v13
	v_cvt_pk_bf16_f32 v11, v14, v15
	s_nop 1
	v_permlane32_swap_b32_e32 v0, v2
	v_permlane32_swap_b32_e32 v1, v3
	v_permlane32_swap_b32_e32 v8, v10
	v_permlane32_swap_b32_e32 v9, v11
	s_nop 1
	v_permlane16_swap_b32_e32 v0, v8
	v_permlane16_swap_b32_e32 v1, v9
	v_permlane16_swap_b32_e32 v2, v10
	v_permlane16_swap_b32_e32 v3, v11
	global_store_dwordx4 v130, v[0:3], s[30:31] offset:448 sc0 sc1
	global_store_dwordx4 v131, v[8:11], s[30:31] offset:448 sc0 sc1
	s_add_i32 s0, s0, s68
	s_add_i32 s33, s33, s28
	s_cmpk_lt_i32 s33, 0x200
	v_readlane_b32 s1, v254, 7
	s_cbranch_scc0 .LBB0_634
